# scan prefetch ring + de-serialised loads in retention/projection/merge/residual epilogues + batched LoRA weight staging
# speedup vs baseline: 1.0458x; 1.0458x over previous
;     DEVINL float* xlead() const { return (float*)(ws + OFF_XL); }
; DEVINL float* xrow(const Ctx& c, int t) {
;     const int b = t / L, p = t - b * L;
;     return p < 128 ? c.xlead() + (size_t)(b * 128 + p) * DM : c.out + ((size_t)b * SEQ + (p - 128)) * DM;
; }
; template <int NI>
; DEVINL void resid_tile(const Ctx& c, const bf16_t* A, int K, const bf16_t* Bt, unsigned char* lds, int m0, int n0, bool dostore) {
;     ...
; #pragma unroll
;     for (int mi = 0; mi < 2; ++mi) {
;         float* xp = xrow(c, mbase + mi * 32 + r) + nbase;
; #pragma unroll
;         for (int ni = 0; ni < NI; ++ni)
; #pragma unroll
;             for (int g = 0; g < 4; ++g) {
;                 f32x4 v = *(f32x4*)(xp + ni * 32 + 8 * g + 4 * h);
; #pragma unroll
;                 for (int j = 0; j < 4; ++j) v[j] += acc[ni][mi][4 * g + j];
;                 if (dostore || v[0] != v[0]) *(f32x4*)(xp + ni * 32 + 8 * g + 4 * h) = v;
;             }
.LBB0_32:
	s_or_b64 exec, exec, s[0:1]
	v_ashrrev_i32_e32 v32, 3, v41
	v_and_b32_e32 v32, 0xffffffe0, v32
	v_add_u32_e32 v32, s4, v32
	v_lshrrev_b32_e32 v39, 3, v40
	v_lshlrev_b64 v[34:35], 12, v[34:35]
	v_ashrrev_i32_e32 v33, 31, v32
	v_and_b32_e32 v39, 4, v39
	v_lshl_add_u64 v[34:35], v[36:37], 0, v[34:35]
	v_lshl_add_u64 v[34:35], v[32:33], 2, v[34:35]
	v_lshlrev_b32_e32 v64, 2, v39
	v_lshl_add_u64 v[40:41], v[34:35], 0, v[64:65]
	global_load_dwordx4 v[168:171], v[40:41], off
	global_load_dwordx4 v[172:175], v[40:41], off offset:32
	global_load_dwordx4 v[176:179], v[40:41], off offset:64
	global_load_dwordx4 v[180:183], v[40:41], off offset:96
	s_mov_b32 s0, 0x78787879
	s_waitcnt vmcnt(3)
	v_pk_add_f32 v[168:169], v[16:17], v[168:169]
	v_pk_add_f32 v[170:171], v[18:19], v[170:171]
	global_store_dwordx4 v[40:41], v[168:171], off
	s_waitcnt vmcnt(3)
	v_pk_add_f32 v[172:173], v[20:21], v[172:173]
	v_pk_add_f32 v[174:175], v[22:23], v[174:175]
	global_store_dwordx4 v[40:41], v[172:175], off offset:32
	s_waitcnt vmcnt(3)
	v_pk_add_f32 v[176:177], v[24:25], v[176:177]
	v_pk_add_f32 v[178:179], v[26:27], v[178:179]
	global_store_dwordx4 v[40:41], v[176:179], off offset:64
	s_waitcnt vmcnt(3)
	v_pk_add_f32 v[180:181], v[28:29], v[180:181]
	v_pk_add_f32 v[182:183], v[30:31], v[182:183]
	global_store_dwordx4 v[40:41], v[180:183], off offset:96
	s_nop 1
	v_or_b32_e32 v17, 32, v38
	v_mul_hi_i32 v16, v17, s0
	v_lshrrev_b32_e32 v18, 31, v16
	v_ashrrev_i32_e32 v16, 10, v16
	v_add_u32_e32 v16, v16, v18
	s_movk_i32 s0, 0xf780
	v_mad_i32_i24 v22, v16, s0, v17
	s_movk_i32 s0, 0x7f
	v_cmp_lt_i32_e32 vcc, s0, v22
	s_and_saveexec_b64 s[0:1], vcc
	s_xor_b64 s[0:1], exec, s[0:1]
	s_cbranch_execz .LBB0_34
	v_ashrrev_i32_e32 v17, 31, v16
	v_readlane_b32 s4, v247, 3
	v_lshlrev_b64 v[16:17], 23, v[16:17]
	v_readlane_b32 s6, v247, 5
	v_readlane_b32 s7, v247, 6
	v_add_u32_e32 v18, 0xffffff80, v22
	v_mov_b32_e32 v19, v65
	v_lshl_add_u64 v[20:21], s[6:7], 0, v[16:17]
	v_readlane_b32 s5, v247, 4

; template <int NI>
; DEVINL void resid_tile(const Ctx& c, const bf16_t* A, int K, const bf16_t* Bt, unsigned char* lds, int m0, int n0, bool dostore) {
;     ...
;     for (int mi = 0; mi < 2; ++mi) {
;         float* xp = xrow(c, mbase + mi * 32 + r) + nbase;
; #pragma unroll
;         for (int ni = 0; ni < NI; ++ni)
; #pragma unroll
;             for (int g = 0; g < 4; ++g) {
;                 f32x4 v = *(f32x4*)(xp + ni * 32 + 8 * g + 4 * h);
; #pragma unroll
;                 for (int j = 0; j < 4; ++j) v[j] += acc[ni][mi][4 * g + j];
;                 if (dostore || v[0] != v[0]) *(f32x4*)(xp + ni * 32 + 8 * g + 4 * h) = v;
;             }
.LBB0_36:
	s_or_b64 exec, exec, s[0:1]
	v_lshlrev_b64 v[16:17], 12, v[18:19]
	v_lshl_add_u64 v[16:17], v[20:21], 0, v[16:17]
	v_lshl_add_u64 v[16:17], v[32:33], 2, v[16:17]
	v_lshl_add_u64 v[20:21], v[16:17], 0, v[64:65]
	global_load_dwordx4 v[168:171], v[20:21], off
	global_load_dwordx4 v[172:175], v[20:21], off offset:32
	global_load_dwordx4 v[176:179], v[20:21], off offset:64
	global_load_dwordx4 v[180:183], v[20:21], off offset:96
	s_waitcnt vmcnt(3)
	v_pk_add_f32 v[168:169], v[0:1], v[168:169]
	v_pk_add_f32 v[170:171], v[2:3], v[170:171]
	global_store_dwordx4 v[20:21], v[168:171], off
	s_waitcnt vmcnt(3)
	v_pk_add_f32 v[172:173], v[4:5], v[172:173]
	v_pk_add_f32 v[174:175], v[6:7], v[174:175]
	global_store_dwordx4 v[20:21], v[172:175], off offset:32
	s_waitcnt vmcnt(3)
	v_pk_add_f32 v[176:177], v[8:9], v[176:177]
	v_pk_add_f32 v[178:179], v[10:11], v[178:179]
	global_store_dwordx4 v[20:21], v[176:179], off offset:64
	s_waitcnt vmcnt(3)
	v_pk_add_f32 v[180:181], v[12:13], v[180:181]
	v_pk_add_f32 v[182:183], v[14:15], v[182:183]
	global_store_dwordx4 v[20:21], v[180:183], off offset:96

; template <int NI>
; DEVINL void resid_tile(const Ctx& c, const bf16_t* A, int K, const bf16_t* Bt, unsigned char* lds, int m0, int n0, bool dostore) {
;     ...
;     for (int mi = 0; mi < 2; ++mi) {
;         float* xp = xrow(c, mbase + mi * 32 + r) + nbase;
; #pragma unroll
;         for (int ni = 0; ni < NI; ++ni)
; #pragma unroll
;             for (int g = 0; g < 4; ++g) {
;                 f32x4 v = *(f32x4*)(xp + ni * 32 + 8 * g + 4 * h);
; #pragma unroll
;                 for (int j = 0; j < 4; ++j) v[j] += acc[ni][mi][4 * g + j];
;                 if (dostore || v[0] != v[0]) *(f32x4*)(xp + ni * 32 + 8 * g + 4 * h) = v;
;             }
; DEVINL void phase_gemm_resid(const Ctx& c, const bf16_t* A, int K, const bf16_t* Bt, unsigned char* lds, bool dostore = true) {
;     ...
;     for (int q = slot; q < (halves ? nfull : total); q += G) {
;         int tm, tn; tile_of(q, MT, NT, tm, tn);
;         resid_tile<2>(c, A, K, Bt, lds, tm * 256, tn * 128, dostore);
;     }
.LBB0_56:
	s_or_b64 exec, exec, s[0:1]
	v_lshlrev_b64 v[32:33], 12, v[34:35]
	v_lshl_add_u64 v[32:33], v[36:37], 0, v[32:33]
	v_lshl_add_u64 v[32:33], v[66:67], 2, v[32:33]
	v_lshl_add_u64 v[36:37], v[32:33], 0, v[64:65]
	global_load_dwordx4 v[168:171], v[36:37], off
	global_load_dwordx4 v[172:175], v[36:37], off offset:32
	global_load_dwordx4 v[176:179], v[36:37], off offset:64
	global_load_dwordx4 v[180:183], v[36:37], off offset:96
	global_load_dwordx4 v[184:187], v[36:37], off offset:128
	global_load_dwordx4 v[188:191], v[36:37], off offset:160
	global_load_dwordx4 v[192:195], v[36:37], off offset:192
	global_load_dwordx4 v[196:199], v[36:37], off offset:224
	s_add_i32 s5, s5, s70
	v_readlane_b32 s0, v246, 10
	s_cmp_ge_i32 s5, s0
	s_waitcnt vmcnt(7)
	v_pk_add_f32 v[168:169], v[16:17], v[168:169]
	v_pk_add_f32 v[170:171], v[18:19], v[170:171]
	global_store_dwordx4 v[36:37], v[168:171], off
	s_waitcnt vmcnt(7)
	v_pk_add_f32 v[172:173], v[20:21], v[172:173]
	v_pk_add_f32 v[174:175], v[22:23], v[174:175]
	global_store_dwordx4 v[36:37], v[172:175], off offset:32
	s_waitcnt vmcnt(7)
	v_pk_add_f32 v[176:177], v[24:25], v[176:177]
	v_pk_add_f32 v[178:179], v[26:27], v[178:179]
	global_store_dwordx4 v[36:37], v[176:179], off offset:64
	s_waitcnt vmcnt(7)
	v_pk_add_f32 v[180:181], v[28:29], v[180:181]
	v_pk_add_f32 v[182:183], v[30:31], v[182:183]
	global_store_dwordx4 v[36:37], v[180:183], off offset:96
	s_waitcnt vmcnt(7)
	v_pk_add_f32 v[184:185], v[0:1], v[184:185]
	v_pk_add_f32 v[186:187], v[2:3], v[186:187]
	global_store_dwordx4 v[36:37], v[184:187], off offset:128
	s_waitcnt vmcnt(7)
	v_pk_add_f32 v[188:189], v[4:5], v[188:189]
	v_pk_add_f32 v[190:191], v[6:7], v[190:191]
	global_store_dwordx4 v[36:37], v[188:191], off offset:160
	s_waitcnt vmcnt(7)
	v_pk_add_f32 v[192:193], v[8:9], v[192:193]
	v_pk_add_f32 v[194:195], v[10:11], v[194:195]
	global_store_dwordx4 v[36:37], v[192:195], off offset:192
	s_waitcnt vmcnt(7)
	v_pk_add_f32 v[196:197], v[12:13], v[196:197]
	v_pk_add_f32 v[198:199], v[14:15], v[198:199]
	global_store_dwordx4 v[36:37], v[196:199], off offset:224
	s_cbranch_scc1 .LBB0_25

;     DEVINL float* xlead() const { return (float*)(ws + OFF_XL); }
; DEVINL float* xrow(const Ctx& c, int t) {
;     const int b = t / L, p = t - b * L;
;     return p < 128 ? c.xlead() + (size_t)(b * 128 + p) * DM : c.out + ((size_t)b * SEQ + (p - 128)) * DM;
; }
; template <int NI>
; DEVINL void resid_tile(const Ctx& c, const bf16_t* A, int K, const bf16_t* Bt, unsigned char* lds, int m0, int n0, bool dostore) {
;     ...
; #pragma unroll
;     for (int mi = 0; mi < 2; ++mi) {
;         float* xp = xrow(c, mbase + mi * 32 + r) + nbase;
; #pragma unroll
;         for (int ni = 0; ni < NI; ++ni)
; #pragma unroll
;             for (int g = 0; g < 4; ++g) {
;                 f32x4 v = *(f32x4*)(xp + ni * 32 + 8 * g + 4 * h);
; #pragma unroll
;                 for (int j = 0; j < 4; ++j) v[j] += acc[ni][mi][4 * g + j];
;                 if (dostore || v[0] != v[0]) *(f32x4*)(xp + ni * 32 + 8 * g + 4 * h) = v;
;             }
.LBB0_63:
	s_or_b64 exec, exec, s[0:1]
	v_ashrrev_i32_e32 v64, 2, v93
	v_and_b32_e32 v64, 0xffffffc0, v64
	v_add_u32_e32 v66, s6, v64
	v_lshrrev_b32_e32 v64, 3, v92
	v_lshlrev_b64 v[68:69], 12, v[68:69]
	v_ashrrev_i32_e32 v67, 31, v66
	v_and_b32_e32 v64, 4, v64
	v_lshl_add_u64 v[68:69], v[70:71], 0, v[68:69]
	v_lshl_add_u64 v[68:69], v[66:67], 2, v[68:69]
	v_lshlrev_b32_e32 v64, 2, v64
	v_lshl_add_u64 v[74:75], v[68:69], 0, v[64:65]
	global_load_dwordx4 v[168:171], v[74:75], off
	global_load_dwordx4 v[172:175], v[74:75], off offset:32
	global_load_dwordx4 v[176:179], v[74:75], off offset:64
	global_load_dwordx4 v[180:183], v[74:75], off offset:96
	global_load_dwordx4 v[184:187], v[74:75], off offset:128
	global_load_dwordx4 v[188:191], v[74:75], off offset:160
	global_load_dwordx4 v[192:195], v[74:75], off offset:192
	global_load_dwordx4 v[196:199], v[74:75], off offset:224
	s_mov_b32 s0, 0x78787879
	s_waitcnt vmcnt(7)
	v_pk_add_f32 v[168:169], v[48:49], v[168:169]
	v_pk_add_f32 v[170:171], v[50:51], v[170:171]
	global_store_dwordx4 v[74:75], v[168:171], off
	s_waitcnt vmcnt(7)
	v_pk_add_f32 v[172:173], v[52:53], v[172:173]
	v_pk_add_f32 v[174:175], v[54:55], v[174:175]
	global_store_dwordx4 v[74:75], v[172:175], off offset:32
	s_waitcnt vmcnt(7)
	v_pk_add_f32 v[176:177], v[56:57], v[176:177]
	v_pk_add_f32 v[178:179], v[58:59], v[178:179]
	global_store_dwordx4 v[74:75], v[176:179], off offset:64
	s_waitcnt vmcnt(7)
	v_pk_add_f32 v[180:181], v[60:61], v[180:181]
	v_pk_add_f32 v[182:183], v[62:63], v[182:183]
	global_store_dwordx4 v[74:75], v[180:183], off offset:96
	s_waitcnt vmcnt(7)
	v_pk_add_f32 v[184:185], v[32:33], v[184:185]
	v_pk_add_f32 v[186:187], v[34:35], v[186:187]
	global_store_dwordx4 v[74:75], v[184:187], off offset:128
	s_waitcnt vmcnt(7)
	v_pk_add_f32 v[188:189], v[36:37], v[188:189]
	v_pk_add_f32 v[190:191], v[38:39], v[190:191]
	global_store_dwordx4 v[74:75], v[188:191], off offset:160
	s_waitcnt vmcnt(7)
	v_pk_add_f32 v[192:193], v[40:41], v[192:193]
	v_pk_add_f32 v[194:195], v[42:43], v[194:195]
	global_store_dwordx4 v[74:75], v[192:195], off offset:192
	s_waitcnt vmcnt(7)
	v_pk_add_f32 v[196:197], v[44:45], v[196:197]
	v_pk_add_f32 v[198:199], v[46:47], v[198:199]
	global_store_dwordx4 v[74:75], v[196:199], off offset:224
	s_nop 1
	v_or_b32_e32 v33, 32, v72
	v_mul_hi_i32 v32, v33, s0
	v_lshrrev_b32_e32 v34, 31, v32
	v_ashrrev_i32_e32 v32, 10, v32
	v_add_u32_e32 v32, v32, v34
	s_movk_i32 s0, 0xf780
	v_mad_i32_i24 v38, v32, s0, v33
	s_movk_i32 s0, 0x7f
	v_cmp_lt_i32_e32 vcc, s0, v38
	s_and_saveexec_b64 s[0:1], vcc
	s_xor_b64 s[0:1], exec, s[0:1]
	s_cbranch_execz .LBB0_65
	v_ashrrev_i32_e32 v33, 31, v32
	v_readlane_b32 s8, v247, 3
	v_lshlrev_b64 v[32:33], 23, v[32:33]
	v_readlane_b32 s10, v247, 5
	v_readlane_b32 s11, v247, 6
	v_add_u32_e32 v34, 0xffffff80, v38
	v_mov_b32_e32 v35, v65
	v_lshl_add_u64 v[36:37], s[10:11], 0, v[32:33]
	v_readlane_b32 s9, v247, 4

;     DEVINL float* xlead() const { return (float*)(ws + OFF_XL); }
; DEVINL float* xrow(const Ctx& c, int t) {
;     const int b = t / L, p = t - b * L;
;     return p < 128 ? c.xlead() + (size_t)(b * 128 + p) * DM : c.out + ((size_t)b * SEQ + (p - 128)) * DM;
; }
; template <int NI>
; DEVINL void resid_tile(const Ctx& c, const bf16_t* A, int K, const bf16_t* Bt, unsigned char* lds, int m0, int n0, bool dostore) {
;     ...
; #pragma unroll
;     for (int mi = 0; mi < 2; ++mi) {
;         float* xp = xrow(c, mbase + mi * 32 + r) + nbase;
; #pragma unroll
;         for (int ni = 0; ni < NI; ++ni)
; #pragma unroll
;             for (int g = 0; g < 4; ++g) {
;                 f32x4 v = *(f32x4*)(xp + ni * 32 + 8 * g + 4 * h);
; #pragma unroll
;                 for (int j = 0; j < 4; ++j) v[j] += acc[ni][mi][4 * g + j];
;                 if (dostore || v[0] != v[0]) *(f32x4*)(xp + ni * 32 + 8 * g + 4 * h) = v;
;             }
.LBB0_77:
	s_or_b64 exec, exec, s[0:1]
	v_ashrrev_i32_e32 v32, 3, v39
	v_and_b32_e32 v32, 0xffffffe0, v32
	v_add_u32_e32 v32, s4, v32
	v_lshrrev_b32_e32 v38, 3, v38
	v_lshlrev_b64 v[34:35], 12, v[34:35]
	v_ashrrev_i32_e32 v33, 31, v32
	v_and_b32_e32 v38, 4, v38
	v_lshl_add_u64 v[34:35], v[36:37], 0, v[34:35]
	v_lshl_add_u64 v[34:35], v[32:33], 2, v[34:35]
	v_lshlrev_b32_e32 v64, 2, v38
	v_lshl_add_u64 v[38:39], v[34:35], 0, v[64:65]
	global_load_dwordx4 v[168:171], v[38:39], off
	global_load_dwordx4 v[172:175], v[38:39], off offset:32
	global_load_dwordx4 v[176:179], v[38:39], off offset:64
	global_load_dwordx4 v[180:183], v[38:39], off offset:96
	s_mov_b32 s0, 0x78787879
	s_waitcnt vmcnt(3)
	v_pk_add_f32 v[168:169], v[16:17], v[168:169]
	v_pk_add_f32 v[170:171], v[18:19], v[170:171]
	global_store_dwordx4 v[38:39], v[168:171], off
	s_waitcnt vmcnt(3)
	v_pk_add_f32 v[172:173], v[20:21], v[172:173]
	v_pk_add_f32 v[174:175], v[22:23], v[174:175]
	global_store_dwordx4 v[38:39], v[172:175], off offset:32
	s_waitcnt vmcnt(3)
	v_pk_add_f32 v[176:177], v[24:25], v[176:177]
	v_pk_add_f32 v[178:179], v[26:27], v[178:179]
	global_store_dwordx4 v[38:39], v[176:179], off offset:64
	s_waitcnt vmcnt(3)
	v_pk_add_f32 v[180:181], v[28:29], v[180:181]
	v_pk_add_f32 v[182:183], v[30:31], v[182:183]
	global_store_dwordx4 v[38:39], v[180:183], off offset:96
	s_nop 1
	v_or_b32_e32 v17, 32, v40
	v_mul_hi_i32 v16, v17, s0
	v_lshrrev_b32_e32 v18, 31, v16
	v_ashrrev_i32_e32 v16, 10, v16
	v_add_u32_e32 v16, v16, v18
	s_movk_i32 s0, 0xf780
	v_mad_i32_i24 v22, v16, s0, v17
	s_movk_i32 s0, 0x7f
	v_cmp_lt_i32_e32 vcc, s0, v22
	s_and_saveexec_b64 s[0:1], vcc
	s_xor_b64 s[0:1], exec, s[0:1]
	s_cbranch_execz .LBB0_79
	v_ashrrev_i32_e32 v17, 31, v16
	v_readlane_b32 s4, v247, 3
	v_lshlrev_b64 v[16:17], 23, v[16:17]
	v_readlane_b32 s6, v247, 5
	v_readlane_b32 s7, v247, 6
	v_add_u32_e32 v18, 0xffffff80, v22
	v_mov_b32_e32 v19, v65
	v_lshl_add_u64 v[20:21], s[6:7], 0, v[16:17]
	v_readlane_b32 s5, v247, 4

; DEVINL bf16_t f2bf(float f) { return (bf16_t)(cvt_pk_bf16(f, 0.f) & 0xffffu); }
; DEVINL void rw_project_head(const Ctx& c, int layer, int b, int hd, int pj, int nP, unsigned* cnt, unsigned char* lds) {
;     ...
;     __syncthreads();
;     {
;         const float* w2 = c.in[I_W2] + (size_t)layer * 64 * 512 + hd * 64;
;         const float* a2 = c.in[I_A2] + (size_t)layer * 64 * 512 + hd * 64;
;         const float* g2 = c.in[I_G2] + (size_t)layer * 128 * 512 + hd * 64;
;         const float* v2 = c.in[I_V2] + (size_t)(layer > 0 ? layer - 1 : 0) * 32 * 512 + hd * 64;
;         for (int e = tid; e < 64 * 288; e += NTHR) {
;             const int k = e >> 6, col = e & 63;
;             float v;
;             if (k < 64) v = w2[(size_t)k * 512 + col];
;             else if (k < 128) v = a2[(size_t)(k - 64) * 512 + col];
;             else if (k < 256) v = g2[(size_t)(k - 128) * 512 + col];
;             else v = layer > 0 ? v2[(size_t)(k - 256) * 512 + col] : 0.f;
;             BW[col * RP_KP + k] = f2bf(v);
.LBB0_101:
	s_lshl_b32 s0, s29, 6
	s_and_b32 s31, s0, 0x1c0
	v_readlane_b32 s0, v247, 1
	v_readlane_b32 s1, v247, 2
	s_cmp_gt_i32 s0, 8
	v_readlane_b32 s0, v245, 32
	s_waitcnt vmcnt(0)
	v_mov_b32_e32 v15, v160
	s_cselect_b64 s[4:5], -1, 0
	s_add_i32 s34, s0, -1
	s_movk_i32 s0, 0x4800
	v_readlane_b32 s1, v245, 33
	v_and_b32_e32 v14, 63, v15
	v_cmp_gt_i32_e32 vcc, s0, v15
	s_waitcnt vmcnt(0)
	s_barrier
	s_and_saveexec_b64 s[0:1], vcc
	s_cbranch_execz .LBB0_131
	s_and_b64 s[6:7], s[4:5], exec
	s_cselect_b32 s66, s34, 0
	v_readlane_b32 s8, v245, 11
	s_lshl_b64 s[6:7], s[66:67], 16
	v_readlane_b32 s10, v245, 13
	v_readlane_b32 s11, v245, 14
	v_readlane_b32 s16, v245, 19
	s_add_u32 s6, s10, s6
	v_readlane_b32 s9, v245, 12
	s_addc_u32 s7, s11, s7
	s_lshl_b32 s16, s31, 2
	v_readlane_b32 s12, v245, 15
	v_readlane_b32 s13, v245, 16
	s_add_u32 s6, s6, s16
	v_readlane_b32 s8, v245, 32
	s_addc_u32 s7, s7, 0
	v_readlane_b32 s9, v245, 33
	s_mov_b32 s12, s8
	s_ashr_i32 s13, s8, 31
	v_readlane_b32 s68, v246, 59
	s_lshl_b64 s[8:9], s[12:13], 18
	v_readlane_b32 s70, v246, 61
	v_readlane_b32 s71, v246, 62
	s_add_u32 s8, s70, s8
	s_addc_u32 s9, s71, s9
	s_mov_b32 s10, s12
	v_readlane_b32 s14, v245, 17
	v_readlane_b32 s15, v245, 18
	v_readlane_b32 s17, v245, 20
	v_readlane_b32 s18, v245, 21
	v_readlane_b32 s19, v245, 22
	v_readlane_b32 s20, v245, 23
	v_readlane_b32 s21, v245, 24
	v_readlane_b32 s22, v245, 25
	v_readlane_b32 s23, v245, 26
	v_readlane_b32 s73, v245, 0
	v_readlane_b32 s74, v245, 1
	v_readlane_b32 s75, v245, 2
	v_readlane_b32 s76, v245, 3
	v_readlane_b32 s77, v245, 4
	v_readlane_b32 s78, v245, 5
	v_readlane_b32 s79, v245, 6
	v_readlane_b32 s80, v245, 7
	v_readlane_b32 s81, v245, 8
	v_readlane_b32 s82, v245, 9
	v_readlane_b32 s83, v245, 10
	s_add_u32 s8, s8, s16
	v_writelane_b32 v245, s10, 32
	s_addc_u32 s9, s9, 0
	v_readlane_b32 s69, v246, 60
	v_writelane_b32 v245, s11, 33
	s_lshl_b64 s[10:11], s[12:13], 17
	s_add_u32 s14, s68, s10
	v_readlane_b32 s72, v246, 63
	s_addc_u32 s15, s69, s11
	s_add_u32 s14, s14, s16
	v_readlane_b32 s68, v246, 43
	s_addc_u32 s15, s15, 0
	v_readlane_b32 s80, v246, 55
	v_readlane_b32 s81, v246, 56
	s_add_u32 s10, s80, s10
	s_addc_u32 s11, s81, s11
	s_add_u32 s10, s10, s16
	v_lshlrev_b32_e32 v64, 2, v14
	s_addc_u32 s11, s11, 0
	v_lshl_add_u64 v[0:1], s[6:7], 0, v[64:65]
	s_movk_i32 s6, 0x250
	v_lshl_add_u64 v[2:3], s[8:9], 0, v[64:65]
	v_lshl_add_u64 v[4:5], s[14:15], 0, v[64:65]
	v_lshl_add_u64 v[6:7], s[10:11], 0, v[64:65]
	v_mad_u32_u24 v16, v14, s6, 0
	s_mov_b64 s[6:7], 0
	v_mov_b32_e32 v17, v15
	v_readlane_b32 s69, v246, 44
	v_readlane_b32 s70, v246, 45
	v_readlane_b32 s71, v246, 46
	v_readlane_b32 s72, v246, 47
	v_readlane_b32 s73, v246, 48
	v_readlane_b32 s74, v246, 49
	v_readlane_b32 s75, v246, 50
	v_readlane_b32 s76, v246, 51
	v_readlane_b32 s77, v246, 52
	v_readlane_b32 s78, v246, 53
	v_readlane_b32 s79, v246, 54
	v_readlane_b32 s82, v246, 57
	v_readlane_b32 s83, v246, 58
	v_lshrrev_b32_e32 v18, 6, v15
	v_lshlrev_b32_e32 v64, 11, v18
	v_lshl_add_u32 v19, v18, 1, v16
	s_mov_b64 s[8:9], 0x4000
	v_lshl_add_u64 v[66:67], v[6:7], 0, v[64:65]
	global_load_dword v20, v[66:67], off
	v_lshl_add_u64 v[66:67], v[66:67], 0, s[8:9]
	global_load_dword v21, v[66:67], off
	v_lshl_add_u64 v[66:67], v[66:67], 0, s[8:9]
	global_load_dword v22, v[66:67], off
	v_lshl_add_u64 v[66:67], v[66:67], 0, s[8:9]
	global_load_dword v23, v[66:67], off
	v_lshl_add_u64 v[66:67], v[66:67], 0, s[8:9]
	global_load_dword v24, v[66:67], off
	v_lshl_add_u64 v[66:67], v[66:67], 0, s[8:9]
	global_load_dword v25, v[66:67], off
	v_lshl_add_u64 v[66:67], v[66:67], 0, s[8:9]
	global_load_dword v26, v[66:67], off
	v_lshl_add_u64 v[66:67], v[66:67], 0, s[8:9]
	global_load_dword v27, v[66:67], off
	v_lshl_add_u64 v[66:67], v[4:5], 0, v[64:65]
	global_load_dword v28, v[66:67], off
	v_lshl_add_u64 v[66:67], v[66:67], 0, s[8:9]
	global_load_dword v29, v[66:67], off
	v_lshl_add_u64 v[66:67], v[66:67], 0, s[8:9]
	global_load_dword v30, v[66:67], off
	v_lshl_add_u64 v[66:67], v[66:67], 0, s[8:9]
	global_load_dword v31, v[66:67], off
	v_lshl_add_u64 v[66:67], v[66:67], 0, s[8:9]
	global_load_dword v32, v[66:67], off
	v_lshl_add_u64 v[66:67], v[66:67], 0, s[8:9]
	global_load_dword v33, v[66:67], off
	v_lshl_add_u64 v[66:67], v[66:67], 0, s[8:9]
	global_load_dword v34, v[66:67], off
	v_lshl_add_u64 v[66:67], v[66:67], 0, s[8:9]
	global_load_dword v35, v[66:67], off
	v_lshl_add_u64 v[66:67], v[2:3], 0, v[64:65]
	global_load_dword v36, v[66:67], off
	v_lshl_add_u64 v[66:67], v[66:67], 0, s[8:9]
	global_load_dword v37, v[66:67], off
	v_lshl_add_u64 v[66:67], v[66:67], 0, s[8:9]
	global_load_dword v38, v[66:67], off
	v_lshl_add_u64 v[66:67], v[66:67], 0, s[8:9]
	global_load_dword v39, v[66:67], off
	v_lshl_add_u64 v[66:67], v[66:67], 0, s[8:9]
	global_load_dword v40, v[66:67], off
	v_lshl_add_u64 v[66:67], v[66:67], 0, s[8:9]
	global_load_dword v41, v[66:67], off
	v_lshl_add_u64 v[66:67], v[66:67], 0, s[8:9]
	global_load_dword v42, v[66:67], off
	v_lshl_add_u64 v[66:67], v[66:67], 0, s[8:9]
	global_load_dword v43, v[66:67], off
	v_lshl_add_u64 v[66:67], v[66:67], 0, s[8:9]
	global_load_dword v44, v[66:67], off
	v_lshl_add_u64 v[66:67], v[66:67], 0, s[8:9]
	global_load_dword v45, v[66:67], off
	v_lshl_add_u64 v[66:67], v[66:67], 0, s[8:9]
	global_load_dword v46, v[66:67], off
	v_lshl_add_u64 v[66:67], v[66:67], 0, s[8:9]
	global_load_dword v47, v[66:67], off
	v_lshl_add_u64 v[66:67], v[66:67], 0, s[8:9]
	global_load_dword v48, v[66:67], off
	v_lshl_add_u64 v[66:67], v[66:67], 0, s[8:9]
	global_load_dword v49, v[66:67], off
	v_lshl_add_u64 v[66:67], v[66:67], 0, s[8:9]
	global_load_dword v50, v[66:67], off
	v_lshl_add_u64 v[66:67], v[66:67], 0, s[8:9]
	global_load_dword v51, v[66:67], off
	v_mov_b32_e32 v52, 0
	v_mov_b32_e32 v53, 0
	v_mov_b32_e32 v54, 0
	v_mov_b32_e32 v55, 0
	s_and_b64 vcc, exec, s[4:5]
	s_cbranch_vccz .Lproj_bw_nov2
	v_lshl_add_u64 v[66:67], v[0:1], 0, v[64:65]
	global_load_dword v52, v[66:67], off
	v_lshl_add_u64 v[66:67], v[66:67], 0, s[8:9]
	global_load_dword v53, v[66:67], off
	v_lshl_add_u64 v[66:67], v[66:67], 0, s[8:9]
	global_load_dword v54, v[66:67], off
	v_lshl_add_u64 v[66:67], v[66:67], 0, s[8:9]
	global_load_dword v55, v[66:67], off
; DEVINL bf16_t f2bf(float f) { return (bf16_t)(cvt_pk_bf16(f, 0.f) & 0xffffu); }
; DEVINL void rw_project_head(const Ctx& c, int layer, int b, int hd, int pj, int nP, unsigned* cnt, unsigned char* lds) {
;     ...
;         for (int e = tid; e < 64 * 288; e += NTHR) {
;             const int k = e >> 6, col = e & 63;
;             float v;
;             if (k < 64) v = w2[(size_t)k * 512 + col];
;             else if (k < 128) v = a2[(size_t)(k - 64) * 512 + col];
;             else if (k < 256) v = g2[(size_t)(k - 128) * 512 + col];
;             else v = layer > 0 ? v2[(size_t)(k - 256) * 512 + col] : 0.f;
;             BW[col * RP_KP + k] = f2bf(v);
;         }
.Lproj_bw_nov2:
	s_waitcnt vmcnt(0)
	v_cvt_pk_bf16_f32 v20, v20, v20
	v_cvt_pk_bf16_f32 v21, v21, v21
	v_cvt_pk_bf16_f32 v22, v22, v22
	v_cvt_pk_bf16_f32 v23, v23, v23
	v_cvt_pk_bf16_f32 v24, v24, v24
	v_cvt_pk_bf16_f32 v25, v25, v25
	v_cvt_pk_bf16_f32 v26, v26, v26
	v_cvt_pk_bf16_f32 v27, v27, v27
	v_cvt_pk_bf16_f32 v28, v28, v28
	v_cvt_pk_bf16_f32 v29, v29, v29
	v_cvt_pk_bf16_f32 v30, v30, v30
	v_cvt_pk_bf16_f32 v31, v31, v31
	v_cvt_pk_bf16_f32 v32, v32, v32
	v_cvt_pk_bf16_f32 v33, v33, v33
	v_cvt_pk_bf16_f32 v34, v34, v34
	v_cvt_pk_bf16_f32 v35, v35, v35
	v_cvt_pk_bf16_f32 v36, v36, v36
	v_cvt_pk_bf16_f32 v37, v37, v37
	v_cvt_pk_bf16_f32 v38, v38, v38
	v_cvt_pk_bf16_f32 v39, v39, v39
	v_cvt_pk_bf16_f32 v40, v40, v40
	v_cvt_pk_bf16_f32 v41, v41, v41
	v_cvt_pk_bf16_f32 v42, v42, v42
	v_cvt_pk_bf16_f32 v43, v43, v43
	v_cvt_pk_bf16_f32 v44, v44, v44
	v_cvt_pk_bf16_f32 v45, v45, v45
	v_cvt_pk_bf16_f32 v46, v46, v46
	v_cvt_pk_bf16_f32 v47, v47, v47
	v_cvt_pk_bf16_f32 v48, v48, v48
	v_cvt_pk_bf16_f32 v49, v49, v49
	v_cvt_pk_bf16_f32 v50, v50, v50
	v_cvt_pk_bf16_f32 v51, v51, v51
	v_cvt_pk_bf16_f32 v52, v52, v52
	v_cvt_pk_bf16_f32 v53, v53, v53
	v_cvt_pk_bf16_f32 v54, v54, v54
	v_cvt_pk_bf16_f32 v55, v55, v55
	ds_write_b16 v19, v20
	ds_write_b16 v19, v21 offset:16
	ds_write_b16 v19, v22 offset:32
	ds_write_b16 v19, v23 offset:48
	ds_write_b16 v19, v24 offset:64
	ds_write_b16 v19, v25 offset:80
	ds_write_b16 v19, v26 offset:96
	ds_write_b16 v19, v27 offset:112
	ds_write_b16 v19, v28 offset:128
	ds_write_b16 v19, v29 offset:144
	ds_write_b16 v19, v30 offset:160
	ds_write_b16 v19, v31 offset:176
	ds_write_b16 v19, v32 offset:192
	ds_write_b16 v19, v33 offset:208
	ds_write_b16 v19, v34 offset:224
	ds_write_b16 v19, v35 offset:240
	ds_write_b16 v19, v36 offset:256
	ds_write_b16 v19, v37 offset:272
	ds_write_b16 v19, v38 offset:288
	ds_write_b16 v19, v39 offset:304
	ds_write_b16 v19, v40 offset:320
	ds_write_b16 v19, v41 offset:336
	ds_write_b16 v19, v42 offset:352
	ds_write_b16 v19, v43 offset:368
	ds_write_b16 v19, v44 offset:384
	ds_write_b16 v19, v45 offset:400
	ds_write_b16 v19, v46 offset:416
	ds_write_b16 v19, v47 offset:432
	ds_write_b16 v19, v48 offset:448
	ds_write_b16 v19, v49 offset:464
	ds_write_b16 v19, v50 offset:480
	ds_write_b16 v19, v51 offset:496
	ds_write_b16 v19, v52 offset:512
	ds_write_b16 v19, v53 offset:528
	ds_write_b16 v19, v54 offset:544
	ds_write_b16 v19, v55 offset:560
	s_branch .LBB0_131

; DEVINL void rw_project_head(const Ctx& c, int layer, int b, int hd, int pj, int nP, unsigned* cnt, unsigned char* lds) {
;     ...
;     float w0c[4], a0c[4], kkc[4], kac[4], v0c[4];
; #pragma unroll
;     for (int nt = 0; nt < 4; ++nt) {
;         const int col = layer * 512 + hd * 64 + nt * 16 + cl;
;         w0c[nt] = c.in[I_W0][col]; a0c[nt] = c.in[I_A0][col]; kkc[nt] = c.in[I_KKW][col]; kac[nt] = c.in[I_KAW][col];
;         v0c[nt] = layer > 0 ? c.in[I_V0][(layer - 1) * 512 + hd * 64 + nt * 16 + cl] : 0.f;
;     }
; template <int NI>
; DEVINL void resid_tile(const Ctx& c, const bf16_t* A, int K, const bf16_t* Bt, unsigned char* lds, int m0, int n0, bool dostore) {
;     ...
;     for (int mi = 0; mi < 2; ++mi) {
;         float* xp = xrow(c, mbase + mi * 32 + r) + nbase;
; #pragma unroll
;         for (int ni = 0; ni < NI; ++ni)
; #pragma unroll
;             for (int g = 0; g < 4; ++g) {
;                 f32x4 v = *(f32x4*)(xp + ni * 32 + 8 * g + 4 * h);
; #pragma unroll
;                 for (int j = 0; j < 4; ++j) v[j] += acc[ni][mi][4 * g + j];
;                 if (dostore || v[0] != v[0]) *(f32x4*)(xp + ni * 32 + 8 * g + 4 * h) = v;
;             }
.LBB0_110:
	s_or_b64 exec, exec, s[0:1]
	v_ashrrev_i32_e32 v64, 2, v95
	v_and_b32_e32 v64, 0xffffffc0, v64
	v_add_u32_e32 v66, s6, v64
	v_lshrrev_b32_e32 v64, 3, v94
	v_lshlrev_b64 v[68:69], 12, v[68:69]
	v_ashrrev_i32_e32 v67, 31, v66
	v_and_b32_e32 v64, 4, v64
	v_lshl_add_u64 v[68:69], v[70:71], 0, v[68:69]
	v_lshl_add_u64 v[68:69], v[66:67], 2, v[68:69]
	v_lshlrev_b32_e32 v64, 2, v64
	v_lshl_add_u64 v[74:75], v[68:69], 0, v[64:65]
	global_load_dwordx4 v[168:171], v[74:75], off
	global_load_dwordx4 v[172:175], v[74:75], off offset:32
	global_load_dwordx4 v[176:179], v[74:75], off offset:64
	global_load_dwordx4 v[180:183], v[74:75], off offset:96
	global_load_dwordx4 v[184:187], v[74:75], off offset:128
	global_load_dwordx4 v[188:191], v[74:75], off offset:160
	global_load_dwordx4 v[192:195], v[74:75], off offset:192
	global_load_dwordx4 v[196:199], v[74:75], off offset:224
	s_mov_b32 s0, 0x78787879
	s_waitcnt vmcnt(7)
	v_pk_add_f32 v[168:169], v[48:49], v[168:169]
	v_pk_add_f32 v[170:171], v[50:51], v[170:171]
	global_store_dwordx4 v[74:75], v[168:171], off
	s_waitcnt vmcnt(7)
	v_pk_add_f32 v[172:173], v[52:53], v[172:173]
	v_pk_add_f32 v[174:175], v[54:55], v[174:175]
	global_store_dwordx4 v[74:75], v[172:175], off offset:32
	s_waitcnt vmcnt(7)
	v_pk_add_f32 v[176:177], v[56:57], v[176:177]
	v_pk_add_f32 v[178:179], v[58:59], v[178:179]
	global_store_dwordx4 v[74:75], v[176:179], off offset:64
	s_waitcnt vmcnt(7)
	v_pk_add_f32 v[180:181], v[60:61], v[180:181]
	v_pk_add_f32 v[182:183], v[62:63], v[182:183]
	global_store_dwordx4 v[74:75], v[180:183], off offset:96
	s_waitcnt vmcnt(7)
	v_pk_add_f32 v[184:185], v[32:33], v[184:185]
	v_pk_add_f32 v[186:187], v[34:35], v[186:187]
	global_store_dwordx4 v[74:75], v[184:187], off offset:128
	s_waitcnt vmcnt(7)
	v_pk_add_f32 v[188:189], v[36:37], v[188:189]
	v_pk_add_f32 v[190:191], v[38:39], v[190:191]
	global_store_dwordx4 v[74:75], v[188:191], off offset:160
	s_waitcnt vmcnt(7)
	v_pk_add_f32 v[192:193], v[40:41], v[192:193]
	v_pk_add_f32 v[194:195], v[42:43], v[194:195]
	global_store_dwordx4 v[74:75], v[192:195], off offset:192
	s_waitcnt vmcnt(7)
	v_pk_add_f32 v[196:197], v[44:45], v[196:197]
	v_pk_add_f32 v[198:199], v[46:47], v[198:199]
	global_store_dwordx4 v[74:75], v[196:199], off offset:224
	s_nop 1
	v_or_b32_e32 v33, 32, v72
	v_mul_hi_i32 v32, v33, s0
	v_lshrrev_b32_e32 v34, 31, v32
	v_ashrrev_i32_e32 v32, 10, v32
	v_add_u32_e32 v32, v32, v34
	s_movk_i32 s0, 0xf780
	v_mad_i32_i24 v38, v32, s0, v33
	s_movk_i32 s0, 0x7f
	v_cmp_lt_i32_e32 vcc, s0, v38
	s_and_saveexec_b64 s[0:1], vcc
	s_xor_b64 s[0:1], exec, s[0:1]
	s_cbranch_execz .LBB0_112
	v_ashrrev_i32_e32 v33, 31, v32
	v_readlane_b32 s8, v247, 3
	v_lshlrev_b64 v[32:33], 23, v[32:33]
	v_readlane_b32 s10, v247, 5
	v_readlane_b32 s11, v247, 6
	v_add_u32_e32 v34, 0xffffff80, v38
	v_mov_b32_e32 v35, v65
	v_lshl_add_u64 v[36:37], s[10:11], 0, v[32:33]
	v_readlane_b32 s9, v247, 4
.LBB0_112:
	s_andn2_saveexec_b64 s[0:1], s[0:1]
	s_cbranch_execz .LBB0_103
	v_readlane_b32 s6, v247, 16
	v_lshl_add_u32 v34, v32, 7, v38
	v_readlane_b32 s7, v247, 17
	v_ashrrev_i32_e32 v35, 31, v34
	s_nop 0
	v_mov_b64_e32 v[36:37], s[6:7]
	s_branch .LBB0_103
.LBB0_131:
	s_or_b64 exec, exec, s[0:1]
	v_readlane_b32 s0, v245, 32
	s_lshl_b32 s0, s0, 9
	v_and_b32_e32 v10, 15, v15
	s_or_b32 s0, s31, s0
	v_or_b32_e32 v0, s0, v10
	v_ashrrev_i32_e32 v1, 31, v0
	v_readlane_b32 s8, v246, 43
	v_lshlrev_b64 v[2:3], 2, v[0:1]
	v_readlane_b32 s9, v246, 44
	v_readlane_b32 s10, v246, 45
	v_readlane_b32 s11, v246, 46
	v_readlane_b32 s12, v246, 47
	v_readlane_b32 s13, v246, 48
	v_readlane_b32 s14, v246, 49
	v_readlane_b32 s15, v246, 50
	v_readlane_b32 s16, v246, 51
	v_readlane_b32 s17, v246, 52
	v_readlane_b32 s18, v246, 53
	v_readlane_b32 s19, v246, 54
	v_readlane_b32 s20, v246, 55
	v_readlane_b32 s21, v246, 56
	v_readlane_b32 s22, v246, 57
	v_readlane_b32 s23, v246, 58
	v_lshl_add_u64 v[0:1], s[18:19], 0, v[2:3]
	global_load_dword v79, v[0:1], off
	v_lshl_add_u64 v[4:5], s[22:23], 0, v[2:3]
	v_readlane_b32 s8, v246, 59
	v_readlane_b32 s12, v246, 63
	v_readlane_b32 s13, v245, 0
	v_readlane_b32 s14, v245, 1
	v_readlane_b32 s15, v245, 2
	v_lshl_add_u64 v[6:7], s[12:13], 0, v[2:3]
	global_load_dword v87, v[4:5], off
	v_lshl_add_u64 v[8:9], s[14:15], 0, v[2:3]
	global_load_dword v113, v[6:7], off
	global_load_dword v115, v[8:9], off
	s_lshl_b32 s0, s34, 9
	s_or_b32 s0, s31, s0
	v_or_b32_e32 v2, s0, v10
	v_mov_b32_e32 v117, 0
	s_and_b64 vcc, exec, s[4:5]
	v_ashrrev_i32_e32 v3, 31, v2
	v_mov_b32_e32 v152, 0
	v_readlane_b32 s1, v245, 33
	v_readlane_b32 s9, v246, 60
	v_readlane_b32 s10, v246, 61
	v_readlane_b32 s11, v246, 62
	v_readlane_b32 s16, v245, 3
	v_readlane_b32 s17, v245, 4
	v_readlane_b32 s18, v245, 5
	v_readlane_b32 s19, v245, 6
	v_readlane_b32 s20, v245, 7
	v_readlane_b32 s21, v245, 8
	v_readlane_b32 s22, v245, 9
	v_readlane_b32 s23, v245, 10
	s_cbranch_vccz .LBB0_133
	v_readlane_b32 s8, v246, 59
	v_readlane_b32 s22, v245, 9
	v_readlane_b32 s23, v245, 10
	v_readlane_b32 s9, v246, 60
	v_readlane_b32 s10, v246, 61
	v_lshl_add_u64 v[12:13], v[2:3], 2, s[22:23]
	global_load_dword v152, v[12:13], off
	v_readlane_b32 s11, v246, 62
	v_readlane_b32 s12, v246, 63
	v_readlane_b32 s13, v245, 0
	v_readlane_b32 s14, v245, 1
	v_readlane_b32 s15, v245, 2
	v_readlane_b32 s16, v245, 3
	v_readlane_b32 s17, v245, 4
	v_readlane_b32 s18, v245, 5
	v_readlane_b32 s19, v245, 6
	v_readlane_b32 s20, v245, 7
	v_readlane_b32 s21, v245, 8

;     DEVINL bf16_t* Z() const { return (bf16_t*)(ws + OFF_Z); }
;     DEVINL bf16_t* RW() const { return (bf16_t*)(ws + OFF_RW); }
; DEVINL void rw_project_head(const Ctx& c, int layer, int b, int hd, int pj, int nP, unsigned* cnt, unsigned char* lds) {
;     ...
;     bf16_t* R = c.RW(); bf16_t* LD = c.RW() + (size_t)T * 512; bf16_t* KP = c.RW() + (size_t)2 * T * 512; bf16_t* VP = c.RW() + (size_t)3 * T * 512;
;     bf16_t* KK = c.RW() + (size_t)4 * T * 512; bf16_t* BB = c.RW() + (size_t)5 * T * 512; bf16_t* GG = c.RW() + (size_t)6 * T * 512;
;     const bf16_t* Zb = c.Z();
;     int round = 0;
;     for (int q0 = 0; nP * q0 + pj < RP_NG; q0 += RP_NW, ++round) {
;         const int g = nP * (q0 + w) + pj;
;         const bool act = (w < RP_NW) && (g < RP_NG);
;         const int t0 = b * L + g * 16;
;         __syncthreads();
;         if (act) {
;             {
;                 const int ch = lane & 31, par = lane >> 5, k = ch * 8;
;                 const f32x4 m0 = *(const f32x4*)(mu + 1536 + k), m1 = *(const f32x4*)(mu + 1536 + k + 4);
;                 const float fa = (ch < 8) ? 1.f : 0.f, fb = (ch < 8) ? -2.f : 1.f, fs = (ch < 8) ? 2.f * LOG2E : -LOG2E;
;                 const bool ident = (ch >= 8 && ch < 16);
;                 u32x4 cu[8], pr[8];
;     ...
;                 u32x4 cu[6], pr[6];
; #pragma unroll
;                 for (int i = 0; i < 6; ++i) {
;                     const int it = lane + 64 * i, tok = it / 24, rem = it - tok * 24, arr = rem >> 3, c8 = (rem & 7) * 8;
;                     const int t = t0 + tok;
;                     const int zcol = Z_C + arr * 512 + hd * 64 + c8;
;                     cu[i] = *(const u32x4*)(Zb + (size_t)t * ZW + zcol);
;                     pr[i] = (u32x4){0u, 0u, 0u, 0u};
;                     if (t - b * L > 0) pr[i] = *(const u32x4*)(Zb + (size_t)(t - 1) * ZW + zcol);
.LBB0_139:
	s_mul_i32 s66, s29, 3
	s_lshr_b32 s18, s29, 3
	s_lshl_b64 s[0:1], s[66:67], 2
	v_readlane_b32 s4, v247, 28
	s_add_u32 s4, s4, s0
	v_readlane_b32 s0, v247, 29
	s_addc_u32 s5, s0, s1
	s_ashr_i32 s29, s28, 31
	s_lshl_b64 s[0:1], s[28:29], 2
	s_add_u32 s8, s4, s0
	v_ashrrev_i32_e32 v6, 6, v15
	s_movk_i32 s0, 0x3d00
	s_addc_u32 s9, s5, s1
	v_mul_lo_u32 v0, v6, s0
	v_readlane_b32 s0, v245, 32
	v_readlane_b32 s1, v245, 33
	s_mov_b32 s12, s0
	s_mulk_i32 s0, 0x700
	s_ashr_i32 s1, s0, 31
	v_readlane_b32 s68, v246, 43
	s_lshl_b64 s[0:1], s[0:1], 2
	v_readlane_b32 s76, v246, 51
	v_cmp_gt_i32_e64 s[6:7], 7, v6
	v_readlane_b32 s77, v246, 52
	s_add_u32 s0, s76, s0
	v_and_b32_e32 v2, 31, v15
	v_cndmask_b32_e64 v0, 0, v0, s[6:7]
	s_addc_u32 s1, s77, s1
	v_lshlrev_b32_e32 v64, 5, v2
	v_add_u32_e32 v7, 0, v0
	v_lshl_add_u64 v[0:1], s[0:1], 0, v[64:65]
	s_mov_b64 s[4:5], 0x1800
	s_sub_i32 s17, 0x88, s28
	v_lshlrev_b32_e32 v78, 3, v2
	v_lshl_add_u64 v[80:81], v[0:1], 0, s[4:5]
	v_cmp_gt_u32_e32 vcc, 8, v2
	v_and_b32_e32 v0, 24, v15
	v_lshl_add_u32 v1, v2, 4, v7
	v_lshlrev_b32_e32 v2, 3, v15
	s_lshl_b32 s10, s31, 2
	v_cmp_eq_u32_e64 s[4:5], 8, v0
	v_lshrrev_b32_e32 v9, 2, v14
	v_and_b32_e32 v0, 24, v2
	v_and_b32_e32 v11, 56, v2
	s_add_u32 s0, s0, s10
	v_mul_u32_u24_e32 v3, 0x250, v9
	v_lshlrev_b32_e32 v4, 1, v0
	v_or_b32_e32 v2, s31, v11
	s_addc_u32 s1, s1, 0
	v_lshlrev_b32_e32 v64, 2, v11
	v_add3_u32 v176, v7, v3, v4
	v_or_b32_e32 v12, 0x800, v2
	v_lshl_add_u64 v[2:3], s[0:1], 0, v[64:65]
	s_movk_i32 s0, 0x250
	v_mad_u32_u24 v177, v10, s0, v7
	s_movk_i32 s0, 0xfdb2
	v_mad_i32_i24 v17, v10, s0, v177
	v_readlane_b32 s0, v247, 1
	v_readlane_b32 s1, v247, 2
	s_mov_b32 s1, 0xaaaaaab
	s_movk_i32 s13, 0xffe8
	v_mul_hi_u32 v18, v14, s1
	v_lshrrev_b32_e32 v4, 2, v15
	v_mad_i32_i24 v19, v18, s13, v14
	v_and_b32_e32 v178, 48, v15
	v_and_b32_e32 v15, 12, v4
	v_lshlrev_b32_e32 v4, 6, v19
	v_and_b32_e32 v4, 0xfffffe00, v4
	v_add_u32_e32 v4, v4, v12
	v_ashrrev_i32_e32 v5, 31, v4
	v_lshl_add_u64 v[88:89], v[4:5], 1, s[26:27]
	v_or_b32_e32 v4, 64, v14
	v_mul_hi_u32 v20, v4, s1
	v_mad_i32_i24 v21, v20, s13, v4
	v_lshlrev_b32_e32 v4, 6, v21
	v_and_b32_e32 v4, 0xfffffe00, v4
	v_add_u32_e32 v4, v4, v12
	v_ashrrev_i32_e32 v5, 31, v4
	v_lshl_add_u64 v[90:91], v[4:5], 1, s[26:27]
	v_or_b32_e32 v4, 0x80, v14
	v_mul_hi_u32 v22, v4, s1
	v_mad_i32_i24 v23, v22, s13, v4
	v_lshlrev_b32_e32 v4, 6, v23
	v_and_b32_e32 v4, 0xfffffe00, v4
	v_add_u32_e32 v4, v4, v12
	v_ashrrev_i32_e32 v5, 31, v4
	v_lshl_add_u64 v[92:93], v[4:5], 1, s[26:27]
	v_or_b32_e32 v4, 0xc0, v14
	v_mul_hi_u32 v24, v4, s1
	v_mad_i32_i24 v25, v24, s13, v4
	v_lshlrev_b32_e32 v4, 6, v25
	v_and_b32_e32 v4, 0xfffffe00, v4
	v_add_u32_e32 v4, v4, v12
	v_ashrrev_i32_e32 v5, 31, v4
	v_lshl_add_u64 v[94:95], v[4:5], 1, s[26:27]
	v_or_b32_e32 v4, 0x100, v14
	v_mul_hi_u32 v26, v4, s1
	v_mad_i32_i24 v27, v26, s13, v4
	v_lshlrev_b32_e32 v4, 6, v27
	v_and_b32_e32 v4, 0xfffffe00, v4
	v_add_u32_e32 v4, v4, v12
	v_ashrrev_i32_e32 v5, 31, v4
	v_lshl_add_u64 v[96:97], v[4:5], 1, s[26:27]
	v_or_b32_e32 v4, 0x140, v14
	v_lshrrev_b32_e32 v8, 5, v14
	v_mul_hi_u32 v14, v4, s1
	v_mad_i32_i24 v28, v14, s13, v4
	v_lshlrev_b32_e32 v4, 6, v28
	v_and_b32_e32 v4, 0xfffffe00, v4
	v_add_u32_e32 v4, v4, v12
	v_ashrrev_i32_e32 v5, 31, v4
	v_ashrrev_i32_e32 v12, 3, v19
	v_lshl_add_u64 v[98:99], v[4:5], 1, s[26:27]
	v_lshlrev_b32_e32 v4, 9, v12
	v_ashrrev_i32_e32 v5, 31, v4
	s_movk_i32 s1, 0x180
	v_lshl_add_u64 v[100:101], v[4:5], 2, v[2:3]
	v_mad_u32_u24 v4, v18, s1, v7
	v_lshlrev_b32_e32 v5, 7, v12
	v_lshlrev_b32_e32 v11, 1, v11
	v_ashrrev_i32_e32 v12, 3, v21
	v_add3_u32 v179, v4, v5, v11
	v_lshlrev_b32_e32 v4, 9, v12
	v_ashrrev_i32_e32 v5, 31, v4
	v_lshl_add_u64 v[102:103], v[4:5], 2, v[2:3]
	v_mad_u32_u24 v4, v20, s1, v7
	v_lshlrev_b32_e32 v5, 7, v12
	v_ashrrev_i32_e32 v12, 3, v23
	v_add3_u32 v180, v4, v5, v11
	v_lshlrev_b32_e32 v4, 9, v12
	v_ashrrev_i32_e32 v5, 31, v4
	v_lshl_add_u64 v[104:105], v[4:5], 2, v[2:3]
	v_mad_u32_u24 v4, v22, s1, v7
	v_lshlrev_b32_e32 v5, 7, v12
	v_ashrrev_i32_e32 v12, 3, v25
	v_add3_u32 v181, v4, v5, v11
	v_lshlrev_b32_e32 v4, 9, v12
	v_ashrrev_i32_e32 v5, 31, v4
	v_lshl_add_u64 v[106:107], v[4:5], 2, v[2:3]
	v_mad_u32_u24 v4, v24, s1, v7
	v_lshlrev_b32_e32 v5, 7, v12
	v_ashrrev_i32_e32 v12, 3, v27
	v_add3_u32 v182, v4, v5, v11
	v_lshlrev_b32_e32 v4, 9, v12
	v_ashrrev_i32_e32 v5, 31, v4
	v_lshl_add_u64 v[108:109], v[4:5], 2, v[2:3]
	v_mad_u32_u24 v4, v26, s1, v7
	v_lshlrev_b32_e32 v5, 7, v12
	v_ashrrev_i32_e32 v12, 3, v28
	v_add3_u32 v183, v4, v5, v11
	v_lshlrev_b32_e32 v4, 9, v12
	v_ashrrev_i32_e32 v5, 31, v4
	s_add_i32 s0, s0, 6
	v_lshl_add_u64 v[110:111], v[4:5], 2, v[2:3]
	v_mad_u32_u24 v2, v14, s1, v7
	v_lshlrev_b32_e32 v3, 7, v12
	s_cmp_gt_u32 s0, 14
	v_add3_u32 v184, v2, v3, v11
	v_mul_lo_u32 v3, s30, v6
	v_readlane_b32 s69, v246, 44
	v_readlane_b32 s70, v246, 45
	v_readlane_b32 s71, v246, 46
	v_readlane_b32 s74, v246, 49
	v_readlane_b32 s75, v246, 50
	v_readlane_b32 s78, v246, 53
	v_readlane_b32 s79, v246, 54
	v_readlane_b32 s80, v246, 55
	v_readlane_b32 s81, v246, 56
	v_readlane_b32 s82, v246, 57
	v_readlane_b32 s83, v246, 58
	s_mulk_i32 s18, 0x880
	v_cndmask_b32_e64 v82, 0, 1.0, vcc
	v_cndmask_b32_e64 v84, 1.0, -2.0, vcc
	v_mul_u32_u24_e32 v13, 0x250, v10
	v_add_u32_e32 v16, 0, v178
	v_or_b32_e32 v86, s31, v10
	s_cselect_b64 s[10:11], -1, 0
	s_lshl_b32 s0, s12, 4
	v_mul_u32_u24_e32 v10, 0x250, v8
	v_mul_u32_u24_e32 v2, 0x180, v15
	v_add_u32_e32 v185, s28, v3
	s_mov_b32 s16, 0
	v_cndmask_b32_e32 v175, v163, v164, vcc
	v_or_b32_e32 v112, 16, v86
	v_or_b32_e32 v114, 32, v86
	v_or_b32_e32 v116, 48, v86
	v_mov_b32_e32 v83, v82
	v_mov_b32_e32 v85, v84
	s_or_b32 s19, s0, 1
	s_mul_i32 s20, s30, 7
	v_lshlrev_b32_e32 v186, 4, v185
	v_or_b32_e32 v187, s18, v14
	s_mul_i32 s21, s30, 0x70
	v_or_b32_e32 v188, s18, v26
	v_or_b32_e32 v189, s18, v24
	v_or_b32_e32 v190, s18, v22
	v_or_b32_e32 v191, s18, v20
	v_or_b32_e32 v192, s18, v18
	v_or_b32_e32 v193, s18, v9
	v_or_b32_e32 v194, s18, v8
	v_or_b32_e32 v195, s18, v15
	v_add_u32_e32 v196, v1, v10
	v_lshlrev_b32_e32 v118, 1, v0
	v_add_u32_e32 v197, v16, v13
	v_add_u32_e32 v198, v17, v2
	s_mov_b64 s[74:75], 0x10000
	s_mov_b64 s[76:77], 0x10080
	s_mov_b64 s[78:79], 0x10100
	s_mov_b64 s[80:81], 0x10180
	s_mov_b64 s[82:83], 0x10200
	s_mov_b64 s[68:69], 0x10280
	s_mov_b64 s[70:71], 0x10300
	v_readlane_b32 s72, v246, 47
	v_readlane_b32 s73, v246, 48
	s_waitcnt lgkmcnt(0)
	s_barrier
	s_branch .LBB0_141

; DEVINL void rw_project_head(const Ctx& c, int layer, int b, int hd, int pj, int nP, unsigned* cnt, unsigned char* lds) {
;     ...
;     for (int q0 = 0; nP * q0 + pj < RP_NG; q0 += RP_NW, ++round) {
;         const int g = nP * (q0 + w) + pj;
;         const bool act = (w < RP_NW) && (g < RP_NG);
;         const int t0 = b * L + g * 16;
;         __syncthreads();
;         if (act) {
;             {
;                 const int ch = lane & 31, par = lane >> 5, k = ch * 8;
;                 const f32x4 m0 = *(const f32x4*)(mu + 1536 + k), m1 = *(const f32x4*)(mu + 1536 + k + 4);
;                 const float fa = (ch < 8) ? 1.f : 0.f, fb = (ch < 8) ? -2.f : 1.f, fs = (ch < 8) ? 2.f * LOG2E : -LOG2E;
;                 const bool ident = (ch >= 8 && ch < 16);
;                 u32x4 cu[8], pr[8];
; #pragma unroll
;                 for (int i = 0; i < 8; ++i) {
;                     const int t = t0 + 2 * i + par;
;                     cu[i] = *(const u32x4*)(Zb + (size_t)t * ZW + Z_C + 1536 + k);
;                     pr[i] = (u32x4){0u, 0u, 0u, 0u};
;                     if (t - b * L > 0) pr[i] = *(const u32x4*)(Zb + (size_t)(t - 1) * ZW + Z_C + 1536 + k);
.LBB0_141:
	v_add_u32_e32 v0, s16, v185
	s_movk_i32 s0, 0x88
	v_cmp_gt_i32_e32 vcc, s0, v0
	s_and_b64 s[0:1], s[6:7], vcc
	s_waitcnt lgkmcnt(0)
	s_nop 0
	s_and_saveexec_b64 s[12:13], s[0:1]
	s_cbranch_execz .LBB0_171
	v_add_u32_e32 v74, v186, v194
	v_mov_b64_e32 v[8:9], s[26:27]
	v_mad_i64_i32 v[8:9], s[14:15], v74, s49, v[8:9]
	v_lshlrev_b32_e32 v64, 1, v78
	v_lshl_add_u64 v[8:9], v[8:9], 0, v[64:65]
	v_add_co_u32_e32 v8, vcc, 0x1000, v8
	global_load_dwordx4 v[0:3], v[80:81], off offset:16
	global_load_dwordx4 v[4:7], v[80:81], off
	v_addc_co_u32_e32 v9, vcc, 0, v9, vcc
	global_load_dwordx4 v[66:69], v[8:9], off offset:3072
	v_cmp_lt_i32_e32 vcc, s18, v74
	v_mov_b32_e32 v56, 0
	v_mov_b32_e32 v70, 0
	v_mov_b32_e32 v71, 0
	v_mov_b32_e32 v72, 0
	v_mov_b32_e32 v73, 0
	s_and_saveexec_b64 s[14:15], vcc
	s_cbranch_execz .LBB0_144
	v_add_u32_e32 v10, -1, v74
	v_mov_b64_e32 v[8:9], s[26:27]
	v_mad_u64_u32 v[8:9], s[24:25], v10, s49, v[8:9]
	v_lshl_add_u64 v[8:9], v[8:9], 0, v[64:65]
	v_add_co_u32_e32 v8, vcc, 0x1000, v8
	s_nop 1
	v_addc_co_u32_e32 v9, vcc, 0, v9, vcc
	global_load_dwordx4 v[70:73], v[8:9], off offset:3072

;     DEVINL bf16_t* VF() const { return (bf16_t*)(ws + OFF_VF); }
; DEVINL void rw_project_head(const Ctx& c, int layer, int b, int hd, int pj, int nP, unsigned* cnt, unsigned char* lds) {
;     ...
;         __syncthreads();
;         if (act) {
;             bf16x8 af[9];
; #pragma unroll
;             for (int ks = 0; ks < 9; ++ks) af[ks] = *(const bf16x8*)(ACT + cl * RP_KP + ks * 32 + kg * 8);
;             float kkraw[4][4], av[4][4], ldv[4][4], gv[4][4], kmod[4][4], vout[4][4], rcv[4][4];
;             float ss[4] = {0.f, 0.f, 0.f, 0.f};
; #pragma unroll
;             for (int nt = 0; nt < 4; ++nt) {
;                 const bf16_t* bp = BW + (nt * 16 + cl) * RP_KP + kg * 8;
;                 f32x4v aw = {0.f, 0.f, 0.f, 0.f}, aa = aw, ag = aw, avv = aw;
;                 aw = MFMA16(af[0], *(const bf16x8*)(bp), aw); aw = MFMA16(af[1], *(const bf16x8*)(bp + 32), aw);
;                 aa = MFMA16(af[2], *(const bf16x8*)(bp + 64), aa); aa = MFMA16(af[3], *(const bf16x8*)(bp + 96), aa);
; #pragma unroll
;                 for (int ks = 4; ks < 8; ++ks) ag = MFMA16(af[ks], *(const bf16x8*)(bp + ks * 32), ag);
;                 avv = MFMA16(af[8], *(const bf16x8*)(bp + 256), avv);
; #pragma unroll
;                 for (int rg = 0; rg < 4; ++rg) {
;                     const int tk = kg * 4 + rg;
;                     const bf16_t* rk = RKV + tk * 192 + nt * 16 + cl;
;                     const float rc = bf2f(rk[0]), kc = bf2f(rk[64]), vc = bf2f(rk[128]);
;                     const float u = -(w0c[nt] + aw[rg]);
;                     const float spl = fmaxf(u, 0.f) + flog2(1.f + fexp2(-fabsf(u) * LOG2E)) * (1.f / LOG2E);
;                     ldv[nt][rg] = -fexp2((-spl - 0.5f) * LOG2E) * LOG2E;
;                     const float a = sigmoidf_(a0c[nt] + aa[rg]);
;                     av[nt][rg] = a; gv[nt][rg] = ag[rg]; rcv[nt][rg] = rc;
;                     const float kr = kc * kkc[nt];
;                     kkraw[nt][rg] = kr; ss[rg] += kr * kr;
;                     kmod[nt][rg] = kc * (1.f + (a - 1.f) * kac[nt]);
;                     const size_t o = (size_t)(t0 + tk) * 512 + hd * 64 + nt * 16 + cl;
;                     float vo = vc;
;                     if (layer == 0) c.VF()[o] = f2bf(vc);
;                     else { const float vf = bf2f(c.VF()[o]); vo = vc + (vf - vc) * sigmoidf_(v0c[nt] + avv[rg]); }
.LBB0_171:
	s_or_b64 exec, exec, s[12:13]
	s_waitcnt lgkmcnt(0)
	s_nop 0
	s_and_saveexec_b64 s[12:13], s[0:1]
	s_cbranch_execz .LBB0_237
	v_readlane_b32 s14, v247, 40
	v_readlane_b32 s15, v247, 41
	v_add_u32_e32 v254, v186, v195
	v_ashrrev_i32_e32 v255, 31, v254
	v_lshlrev_b64 v[254:255], 9, v[254:255]
	v_or_b32_e32 v254, v254, v86
	v_lshl_add_u64 v[254:255], v[254:255], 1, s[14:15]
	s_and_b64 vcc, exec, s[10:11]
	s_cbranch_vccz .Lproj_novf
	global_load_ushort v248, v[254:255], off
	global_load_ushort v249, v[254:255], off offset:1024
	global_load_ushort v250, v[254:255], off offset:2048
	global_load_ushort v251, v[254:255], off offset:3072
	global_load_ushort v252, v[254:255], off offset:32
	global_load_ushort v253, v[254:255], off offset:1056
	global_load_ushort v166, v[254:255], off offset:2080
	global_load_ushort v167, v[254:255], off offset:3104
	global_load_ushort v161, v[254:255], off offset:64
	global_load_ushort v162, v[254:255], off offset:1088
	global_load_ushort v165, v[254:255], off offset:2112
	global_load_ushort v238, v[254:255], off offset:3136
	global_load_ushort v239, v[254:255], off offset:96
	global_load_ushort v240, v[254:255], off offset:1120
	global_load_ushort v241, v[254:255], off offset:2144
	global_load_ushort v254, v[254:255], off offset:3168

; DEVINL void rw_project_head(const Ctx& c, int layer, int b, int hd, int pj, int nP, unsigned* cnt, unsigned char* lds) {
;     ...
;         asm volatile("s_waitcnt vmcnt(0)" ::: "memory");
;         __syncthreads();
;         if (threadIdx.x == 0) {
;             __builtin_amdgcn_fence(__ATOMIC_RELEASE, "agent");
;             __hip_atomic_store(cnt, (unsigned)(layer * 16 + round + 1), __ATOMIC_RELAXED, __HIP_MEMORY_SCOPE_AGENT);
;         }
.LBB0_237:
	s_or_b64 exec, exec, s[12:13]
	s_waitcnt vmcnt(0)
	s_waitcnt vmcnt(63) expcnt(7) lgkmcnt(15)
	s_barrier
	s_mov_b64 s[0:1], exec
	v_cmp_eq_u32_e32 vcc, 0x1c0, v160
	s_nop 0
	s_and_b64 s[12:13], s[0:1], vcc
	s_mov_b64 exec, s[12:13]
	s_cbranch_execz .LBB0_140
	v_mov_b32_e32 v0, s19
	buffer_wbl2 sc1
	s_waitcnt vmcnt(0)
	global_store_dword v65, v0, s[8:9] sc1
	s_branch .LBB0_140
.Ltramp_14:
	s_branch .LBB0_14

; DEVINL void rw_stage_load(u32x4 (&raw)[4], const bf16_t* rwbase, int t0, int hd, int ht) {
;     const int rem = ht & 127, tt = rem >> 3, c8 = rem & 7;
; #pragma unroll
;     for (int k = 0; k < 4; ++k) {
;         const int arr = (ht >> 7) + 2 * k;
;         if (arr < 7) raw[k] = *(const u32x4*)(rwbase + (size_t)arr * T * 512 + (size_t)(t0 + tt) * 512 + hd * 64 + c8 * 8);
;     }
; }
; DEVINL void rwkv_scan(const Ctx& c, int layer, int b, int hd, const unsigned* cnt3, int nP, float* lds) {
;     ...
;     unsigned have = (unsigned)(layer * 16 + 1);
;     rw_wait_ready(cnt3, have, nP);
;     rw_stage(rwbase, b * L, hd, lds, tid, NTHR);
;     u32x4 raw[4];
; #pragma unroll
;     for (int k = 0; k < 4; ++k) raw[k] = (u32x4){0u, 0u, 0u, 0u};
;     if (w >= 4) rw_stage_load(raw, rwbase, b * L + TC, hd, tid - 256);
;     __syncthreads();
.LBB0_315:
	s_or_b64 exec, exec, s[4:5]
	v_lshrrev_b32_e32 v23, 2, v146
	s_movk_i32 s6, 0x280
	v_lshlrev_b32_e32 v24, 4, v150
	v_and_b32_e32 v23, 14, v23
	v_cmp_gt_u32_e64 s[8:9], s6, v21
	s_movk_i32 s6, 0x180
	v_and_or_b32 v153, v24, 48, v23
	s_or_b32 s36, s10, 1
	v_readlane_b32 s4, v246, 31
	v_lshlrev_b32_e32 v23, 5, v21
	v_cmp_gt_u32_e64 s[10:11], s6, v21
	v_readlane_b32 s6, v245, 28
	v_lshl_add_u32 v154, v153, 2, s4
	v_and_b32_e32 v24, 0xf00, v23
	v_and_b32_e32 v23, 0xe0, v23
	s_movk_i32 s4, 0x380
	v_lshlrev_b64 v[18:19], 1, v[18:19]
	v_readlane_b32 s7, v245, 29
	v_add3_u32 v156, 0, v24, v23
	v_cmp_gt_u32_e64 s[4:5], s4, v21
	v_cmp_ne_u32_e64 s[22:23], 1, v22
	v_lshlrev_b32_e32 v157, 12, v22
	v_cmp_gt_u32_e64 s[12:13], s39, v21
	v_ashrrev_i32_e32 v21, 7, v21
	v_lshl_add_u64 v[22:23], s[6:7], 0, v[18:19]
	v_lshl_add_u64 v[134:135], v[16:17], 1, v[22:23]
	s_mov_b32 s6, 0x1100000
	v_add_u32_e32 v16, 2, v21
	v_mad_i64_i32 v[138:139], s[18:19], v16, s6, 0
	v_add_u32_e32 v16, 4, v21
	v_mad_i64_i32 v[140:141], s[20:21], v16, s6, 0
	v_add_u32_e32 v16, 6, v21
	v_mad_i64_i32 v[142:143], s[24:25], v16, s6, 0
	v_readlane_b32 s24, v247, 24
	v_readlane_b32 s25, v247, 25
	s_mul_i32 s37, s34, 7
	v_lshlrev_b32_e32 v64, 1, v20
	v_lshl_add_u64 v[16:17], s[24:25], 0, v[18:19]
	v_lshl_add_u64 v[144:145], v[16:17], 0, v[64:65]
	v_cvt_f32_ubyte0_e32 v17, s37
	v_rcp_iflag_f32_e32 v17, v17
	s_sub_i32 s24, 0, s37
	v_add_u32_e32 v155, -4, v150
	v_add_u32_e32 v158, 4, v150
	v_mul_f32_e32 v17, 0x4f7ffffe, v17
	v_cvt_u32_f32_e32 v17, v17
	v_add_u32_e32 v159, 8, v150
	v_mad_i64_i32 v[136:137], s[16:17], v21, s6, 0
	v_readfirstlane_b32 s25, v17
	s_mul_i32 s24, s24, s25
	v_lshl_or_b32 v16, v155, 6, v20
	v_lshl_or_b32 v18, v158, 6, v20
	v_lshl_or_b32 v19, v159, 6, v20
	s_mul_hi_u32 s24, s25, s24
	v_mov_b32_e32 v64, v65
	v_cmp_lt_i32_e64 s[0:1], 3, v150
	v_cmp_gt_i32_e64 s[14:15], 7, v21
	v_cmp_gt_i32_e64 s[16:17], 5, v21
	v_cmp_gt_i32_e64 s[18:19], 3, v21
	v_cmp_gt_i32_e64 s[20:21], 1, v21
	s_mov_b32 s38, 0
	s_add_i32 s39, s25, s24
	v_mov_b32_e32 v171, s36
	v_lshlrev_b32_e32 v168, 2, v16
	v_lshlrev_b32_e32 v169, 2, v18
	v_lshlrev_b32_e32 v170, 2, v19
	v_mov_b64_e32 v[24:25], v[64:65]
	v_mov_b64_e32 v[26:27], v[64:65]
	v_mov_b64_e32 v[40:41], v[64:65]
	v_mov_b64_e32 v[42:43], v[64:65]
	v_mov_b64_e32 v[44:45], v[64:65]
	v_mov_b64_e32 v[46:47], v[64:65]
	v_mov_b64_e32 v[60:61], v[64:65]
	v_mov_b64_e32 v[28:29], v[64:65]
	s_mov_b64 s[28:29], exec
	s_and_b64 exec, exec, s[0:1]
	s_cbranch_execz .Lsl_pro_done
	v_add_u32_e32 v16, 32, v151
	v_ashrrev_i32_e32 v17, 31, v16
	v_lshlrev_b64 v[16:17], 10, v[16:17]
	v_lshl_add_u64 v[16:17], v[134:135], 0, v[16:17]
.Lsl_p2:
	s_and_saveexec_b64 s[26:27], s[14:15]
	s_cbranch_execz .Lsl_p2_0
	v_lshl_add_u64 v[68:69], v[16:17], 0, v[136:137]
	global_load_dwordx4 v[68:71], v[68:69], off
.Lsl_p2_0:
	s_or_b64 exec, exec, s[26:27]
	s_and_saveexec_b64 s[26:27], s[16:17]
	s_cbranch_execz .Lsl_p2_1
	v_lshl_add_u64 v[72:73], v[16:17], 0, v[138:139]
	global_load_dwordx4 v[72:75], v[72:73], off
.Lsl_p2_1:
	s_or_b64 exec, exec, s[26:27]
	s_and_saveexec_b64 s[26:27], s[18:19]
	s_cbranch_execz .Lsl_p2_2
	v_lshl_add_u64 v[76:77], v[16:17], 0, v[140:141]
	global_load_dwordx4 v[76:79], v[76:77], off
.Lsl_p2_2:
	s_or_b64 exec, exec, s[26:27]
	s_and_saveexec_b64 s[26:27], s[20:21]
	s_cbranch_execz .Lsl_p2_3
	v_lshl_add_u64 v[80:81], v[16:17], 0, v[142:143]
	global_load_dwordx4 v[80:83], v[80:81], off
.Lsl_p2_3:
	s_or_b64 exec, exec, s[26:27]
	v_add_u32_e32 v16, 48, v151
	v_ashrrev_i32_e32 v17, 31, v16
	v_lshlrev_b64 v[16:17], 10, v[16:17]
	v_lshl_add_u64 v[16:17], v[134:135], 0, v[16:17]
.Lsl_p3:
	s_and_saveexec_b64 s[26:27], s[14:15]
	s_cbranch_execz .Lsl_p3_0
	v_lshl_add_u64 v[84:85], v[16:17], 0, v[136:137]
	global_load_dwordx4 v[84:87], v[84:85], off
.Lsl_p3_0:
	s_or_b64 exec, exec, s[26:27]
	s_and_saveexec_b64 s[26:27], s[16:17]
	s_cbranch_execz .Lsl_p3_1
	v_lshl_add_u64 v[88:89], v[16:17], 0, v[138:139]
	global_load_dwordx4 v[88:91], v[88:89], off
.Lsl_p3_1:
	s_or_b64 exec, exec, s[26:27]
	s_and_saveexec_b64 s[26:27], s[18:19]
	s_cbranch_execz .Lsl_p3_2
	v_lshl_add_u64 v[92:93], v[16:17], 0, v[140:141]
	global_load_dwordx4 v[92:95], v[92:93], off
.Lsl_p3_2:
	s_or_b64 exec, exec, s[26:27]
	s_and_saveexec_b64 s[26:27], s[20:21]
	s_cbranch_execz .Lsl_p3_3
	v_lshl_add_u64 v[96:97], v[16:17], 0, v[142:143]
	global_load_dwordx4 v[96:99], v[96:97], off
.Lsl_p3_3:
	s_or_b64 exec, exec, s[26:27]
	v_add_u32_e32 v16, 64, v151
	v_ashrrev_i32_e32 v17, 31, v16
	v_lshlrev_b64 v[16:17], 10, v[16:17]
	v_lshl_add_u64 v[16:17], v[134:135], 0, v[16:17]
.Lsl_p4:
	s_and_saveexec_b64 s[26:27], s[14:15]
	s_cbranch_execz .Lsl_p4_0
	v_lshl_add_u64 v[100:101], v[16:17], 0, v[136:137]
	global_load_dwordx4 v[100:103], v[100:101], off
.Lsl_p4_0:
	s_or_b64 exec, exec, s[26:27]
	s_and_saveexec_b64 s[26:27], s[16:17]
	s_cbranch_execz .Lsl_p4_1
	v_lshl_add_u64 v[104:105], v[16:17], 0, v[138:139]
	global_load_dwordx4 v[104:107], v[104:105], off
.Lsl_p4_1:
	s_or_b64 exec, exec, s[26:27]
	s_and_saveexec_b64 s[26:27], s[18:19]
	s_cbranch_execz .Lsl_p4_2
	v_lshl_add_u64 v[108:109], v[16:17], 0, v[140:141]
	global_load_dwordx4 v[108:111], v[108:109], off
.Lsl_p4_2:
	s_or_b64 exec, exec, s[26:27]
	s_and_saveexec_b64 s[26:27], s[20:21]
	s_cbranch_execz .Lsl_p4_3
	v_lshl_add_u64 v[112:113], v[16:17], 0, v[142:143]
	global_load_dwordx4 v[112:115], v[112:113], off

; DEVINL void rwkv_scan(const Ctx& c, int layer, int b, int hd, const unsigned* cnt3, int nP, float* lds) {
;     ...
;     __syncthreads();
.Lsl_pro_done:
	s_mov_b64 exec, s[28:29]
	s_waitcnt lgkmcnt(0)
	s_barrier
	s_branch .LBB0_317

; DEVINL float bflo(unsigned u) { return __uint_as_float(u << 16); }
; DEVINL float bfhi(unsigned u) { return __uint_as_float(u & 0xffff0000u); }
; DEVINL float fexp2(float x) { return __builtin_amdgcn_exp2f(x); }
; DEVINL void rw_stage_write(const u32x4 (&raw)[4], float* buf, int ht) {
;     const int rem = ht & 127, tt = rem >> 3, c8 = rem & 7;
; #pragma unroll
;     for (int k = 0; k < 4; ++k) {
;         const int arr = (ht >> 7) + 2 * k;
;         if (arr < 7) {
;             f32x4 lo = {bflo(raw[k][0]), bfhi(raw[k][0]), bflo(raw[k][1]), bfhi(raw[k][1])}, hi = {bflo(raw[k][2]), bfhi(raw[k][2]), bflo(raw[k][3]), bfhi(raw[k][3])};
;             if (arr == 1) {
; #pragma unroll
;                 for (int j = 0; j < 4; ++j) { lo[j] = fexp2(lo[j]); hi[j] = fexp2(hi[j]); }
;             }
;             float* d = buf + arr * TC * 64 + tt * 64 + c8 * 8;
;             *(f32x4*)d = lo; *(f32x4*)(d + 4) = hi;
;         }
;     }
; }
; DEVINL void rwkv_scan(const Ctx& c, int layer, int b, int hd, const unsigned* cnt3, int nP, float* lds) {
;     ...
;             if (ch + 1 < NCH) rw_stage_write(raw, lds + ((ch + 1) % 3) * STG, ht);
.LBB0_317:
	s_and_saveexec_b64 s[24:25], s[0:1]
	s_xor_b64 s[24:25], exec, s[24:25]
	s_cbranch_execz .LBB0_338
	s_cmpk_gt_u32 s38, 0x86
	s_cbranch_scc1 .LBB0_325
	s_add_i32 s26, s38, 1
	s_and_b32 s27, s26, 0xff
	s_mulk_i32 s27, 0xab
	s_bfe_u32 s27, s27, 0x70009
	s_mul_i32 s27, s27, 3
	s_sub_i32 s26, s26, s27
	s_and_b32 s26, s26, 0xff
	s_mulk_i32 s26, 0x7000
	v_add_u32_e32 v30, s26, v156
	s_cmpk_gt_u32 s38, 130
	s_cbranch_scc1 .Lsw_w0
	s_cmp_gt_u32 s38, 4
	s_cbranch_scc1 .Lsw_w25
	s_cmp_gt_u32 s38, 1
	s_cbranch_scc0 .Lsw_w9
	s_cmp_eq_u32 s38, 2
	s_cbranch_scc1 .Lsw_w13
	s_cmp_eq_u32 s38, 3
	s_cbranch_scc1 .Lsw_w17
	s_waitcnt vmcnt(21)
	s_branch .Lsw_wd
.Lsw_w0:
	s_waitcnt vmcnt(0)
	s_branch .Lsw_wd
.Lsw_w25:
	s_waitcnt vmcnt(25)
	s_branch .Lsw_wd
.Lsw_w9:
	s_waitcnt vmcnt(9)
	s_branch .Lsw_wd
.Lsw_w13:
	s_waitcnt vmcnt(13)
	s_branch .Lsw_wd
.Lsw_w17:
	s_waitcnt vmcnt(17)
.Lsw_wd:
	s_and_b32 s27, s38, 3
	s_cmp_eq_u32 s27, 0
	s_cbranch_scc1 .Lsw_0
	s_cmp_eq_u32 s27, 1
	s_cbranch_scc1 .Lsw_1
	s_cmp_eq_u32 s27, 2
	s_cbranch_scc1 .Lsw_2
	s_branch .Lsw_3
.Lsw_0:
	s_and_saveexec_b64 s[26:27], s[4:5]
	s_cbranch_execz .Lsw_0_k1
	v_lshlrev_b32_e32 v16, 16, v0
	v_and_b32_e32 v17, 0xffff0000, v0
	v_lshlrev_b32_e32 v18, 16, v1
	v_and_b32_e32 v19, 0xffff0000, v1
	v_lshlrev_b32_e32 v20, 16, v2
	v_and_b32_e32 v21, 0xffff0000, v2
	v_lshlrev_b32_e32 v22, 16, v3
	v_and_b32_e32 v23, 0xffff0000, v3
	s_and_saveexec_b64 s[28:29], s[22:23]
	s_xor_b64 s[28:29], exec, s[28:29]
	s_andn2_saveexec_b64 s[28:29], s[28:29]
	s_cbranch_execz .Lsw_0_noexp
	v_exp_f32_e32 v16, v16
	v_exp_f32_e32 v20, v20
	v_exp_f32_e32 v17, v17
	v_exp_f32_e32 v21, v21
	v_exp_f32_e32 v18, v18
	v_exp_f32_e32 v22, v22
	v_exp_f32_e32 v19, v19
	v_exp_f32_e32 v23, v23

; DEVINL float bflo(unsigned u) { return __uint_as_float(u << 16); }
; DEVINL float bfhi(unsigned u) { return __uint_as_float(u & 0xffff0000u); }
; DEVINL float fexp2(float x) { return __builtin_amdgcn_exp2f(x); }
; DEVINL void rw_stage_write(const u32x4 (&raw)[4], float* buf, int ht) {
;     const int rem = ht & 127, tt = rem >> 3, c8 = rem & 7;
; #pragma unroll
;     for (int k = 0; k < 4; ++k) {
;         const int arr = (ht >> 7) + 2 * k;
;         if (arr < 7) {
;             f32x4 lo = {bflo(raw[k][0]), bfhi(raw[k][0]), bflo(raw[k][1]), bfhi(raw[k][1])}, hi = {bflo(raw[k][2]), bfhi(raw[k][2]), bflo(raw[k][3]), bfhi(raw[k][3])};
;             if (arr == 1) {
; #pragma unroll
;                 for (int j = 0; j < 4; ++j) { lo[j] = fexp2(lo[j]); hi[j] = fexp2(hi[j]); }
;             }
;             float* d = buf + arr * TC * 64 + tt * 64 + c8 * 8;
;             *(f32x4*)d = lo; *(f32x4*)(d + 4) = hi;
;         }
;     }
; }
.Lsw_0_k1:
	s_or_b64 exec, exec, s[26:27]
	v_add_u32_e32 v16, v30, v157
	s_and_saveexec_b64 s[26:27], s[8:9]
	s_cbranch_execz .Lsw_0_k2
	v_lshlrev_b32_e32 v18, 16, v4
	v_and_b32_e32 v19, 0xffff0000, v4
	v_lshlrev_b32_e32 v20, 16, v5
	v_and_b32_e32 v21, 0xffff0000, v5
	v_lshlrev_b32_e32 v32, 16, v6
	v_and_b32_e32 v33, 0xffff0000, v6
	v_lshlrev_b32_e32 v34, 16, v7
	v_and_b32_e32 v35, 0xffff0000, v7
	ds_write_b128 v16, v[18:21] offset:8192
	ds_write_b128 v16, v[32:35] offset:8208
.Lsw_0_k2:
	s_or_b64 exec, exec, s[26:27]
	s_and_saveexec_b64 s[26:27], s[10:11]
	s_cbranch_execz .Lsw_0_k3
	v_lshlrev_b32_e32 v18, 16, v8
	v_and_b32_e32 v19, 0xffff0000, v8
	v_lshlrev_b32_e32 v20, 16, v9
	v_and_b32_e32 v21, 0xffff0000, v9
	v_lshlrev_b32_e32 v32, 16, v10
	v_and_b32_e32 v33, 0xffff0000, v10
	v_lshlrev_b32_e32 v34, 16, v11
	v_and_b32_e32 v35, 0xffff0000, v11
	ds_write_b128 v16, v[18:21] offset:16384
	ds_write_b128 v16, v[32:35] offset:16400
.Lsw_0_k3:
	s_or_b64 exec, exec, s[26:27]
	s_and_saveexec_b64 s[26:27], s[12:13]
	s_cbranch_execz .Lsw_0_end
	v_lshlrev_b32_e32 v16, 16, v12
	v_and_b32_e32 v17, 0xffff0000, v12
	v_lshlrev_b32_e32 v18, 16, v13
	v_and_b32_e32 v19, 0xffff0000, v13
	v_lshlrev_b32_e32 v20, 16, v14
	v_and_b32_e32 v21, 0xffff0000, v14
	v_lshlrev_b32_e32 v22, 16, v15
	v_and_b32_e32 v23, 0xffff0000, v15
	ds_write_b128 v30, v[16:19] offset:24576
	ds_write_b128 v30, v[20:23] offset:24592
.Lsw_0_end:
	s_or_b64 exec, exec, s[26:27]
	s_branch .LBB0_335
.Lsw_1:
	s_and_saveexec_b64 s[26:27], s[4:5]
	s_cbranch_execz .Lsw_1_k1
	v_lshlrev_b32_e32 v16, 16, v68
	v_and_b32_e32 v17, 0xffff0000, v68
	v_lshlrev_b32_e32 v18, 16, v69
	v_and_b32_e32 v19, 0xffff0000, v69
	v_lshlrev_b32_e32 v20, 16, v70
	v_and_b32_e32 v21, 0xffff0000, v70
	v_lshlrev_b32_e32 v22, 16, v71
	v_and_b32_e32 v23, 0xffff0000, v71
	s_and_saveexec_b64 s[28:29], s[22:23]
	s_xor_b64 s[28:29], exec, s[28:29]
	s_andn2_saveexec_b64 s[28:29], s[28:29]
	s_cbranch_execz .Lsw_1_noexp
	v_exp_f32_e32 v16, v16
	v_exp_f32_e32 v20, v20
	v_exp_f32_e32 v17, v17
	v_exp_f32_e32 v21, v21
	v_exp_f32_e32 v18, v18
	v_exp_f32_e32 v22, v22
	v_exp_f32_e32 v19, v19
	v_exp_f32_e32 v23, v23

; DEVINL float bflo(unsigned u) { return __uint_as_float(u << 16); }
; DEVINL float bfhi(unsigned u) { return __uint_as_float(u & 0xffff0000u); }
; DEVINL float fexp2(float x) { return __builtin_amdgcn_exp2f(x); }
; DEVINL void rw_stage_write(const u32x4 (&raw)[4], float* buf, int ht) {
;     const int rem = ht & 127, tt = rem >> 3, c8 = rem & 7;
; #pragma unroll
;     for (int k = 0; k < 4; ++k) {
;         const int arr = (ht >> 7) + 2 * k;
;         if (arr < 7) {
;             f32x4 lo = {bflo(raw[k][0]), bfhi(raw[k][0]), bflo(raw[k][1]), bfhi(raw[k][1])}, hi = {bflo(raw[k][2]), bfhi(raw[k][2]), bflo(raw[k][3]), bfhi(raw[k][3])};
;             if (arr == 1) {
; #pragma unroll
;                 for (int j = 0; j < 4; ++j) { lo[j] = fexp2(lo[j]); hi[j] = fexp2(hi[j]); }
;             }
;             float* d = buf + arr * TC * 64 + tt * 64 + c8 * 8;
;             *(f32x4*)d = lo; *(f32x4*)(d + 4) = hi;
;         }
;     }
; }
.Lsw_1_k1:
	s_or_b64 exec, exec, s[26:27]
	v_add_u32_e32 v16, v30, v157
	s_and_saveexec_b64 s[26:27], s[8:9]
	s_cbranch_execz .Lsw_1_k2
	v_lshlrev_b32_e32 v18, 16, v72
	v_and_b32_e32 v19, 0xffff0000, v72
	v_lshlrev_b32_e32 v20, 16, v73
	v_and_b32_e32 v21, 0xffff0000, v73
	v_lshlrev_b32_e32 v32, 16, v74
	v_and_b32_e32 v33, 0xffff0000, v74
	v_lshlrev_b32_e32 v34, 16, v75
	v_and_b32_e32 v35, 0xffff0000, v75
	ds_write_b128 v16, v[18:21] offset:8192
	ds_write_b128 v16, v[32:35] offset:8208
.Lsw_1_k2:
	s_or_b64 exec, exec, s[26:27]
	s_and_saveexec_b64 s[26:27], s[10:11]
	s_cbranch_execz .Lsw_1_k3
	v_lshlrev_b32_e32 v18, 16, v76
	v_and_b32_e32 v19, 0xffff0000, v76
	v_lshlrev_b32_e32 v20, 16, v77
	v_and_b32_e32 v21, 0xffff0000, v77
	v_lshlrev_b32_e32 v32, 16, v78
	v_and_b32_e32 v33, 0xffff0000, v78
	v_lshlrev_b32_e32 v34, 16, v79
	v_and_b32_e32 v35, 0xffff0000, v79
	ds_write_b128 v16, v[18:21] offset:16384
	ds_write_b128 v16, v[32:35] offset:16400
.Lsw_1_k3:
	s_or_b64 exec, exec, s[26:27]
	s_and_saveexec_b64 s[26:27], s[12:13]
	s_cbranch_execz .Lsw_1_end
	v_lshlrev_b32_e32 v16, 16, v80
	v_and_b32_e32 v17, 0xffff0000, v80
	v_lshlrev_b32_e32 v18, 16, v81
	v_and_b32_e32 v19, 0xffff0000, v81
	v_lshlrev_b32_e32 v20, 16, v82
	v_and_b32_e32 v21, 0xffff0000, v82
	v_lshlrev_b32_e32 v22, 16, v83
	v_and_b32_e32 v23, 0xffff0000, v83
	ds_write_b128 v30, v[16:19] offset:24576
	ds_write_b128 v30, v[20:23] offset:24592

; DEVINL float bflo(unsigned u) { return __uint_as_float(u << 16); }
; DEVINL float bfhi(unsigned u) { return __uint_as_float(u & 0xffff0000u); }
; DEVINL float fexp2(float x) { return __builtin_amdgcn_exp2f(x); }
; DEVINL void rw_stage_write(const u32x4 (&raw)[4], float* buf, int ht) {
;     const int rem = ht & 127, tt = rem >> 3, c8 = rem & 7;
; #pragma unroll
;     for (int k = 0; k < 4; ++k) {
;         const int arr = (ht >> 7) + 2 * k;
;         if (arr < 7) {
;             f32x4 lo = {bflo(raw[k][0]), bfhi(raw[k][0]), bflo(raw[k][1]), bfhi(raw[k][1])}, hi = {bflo(raw[k][2]), bfhi(raw[k][2]), bflo(raw[k][3]), bfhi(raw[k][3])};
;             if (arr == 1) {
; #pragma unroll
;                 for (int j = 0; j < 4; ++j) { lo[j] = fexp2(lo[j]); hi[j] = fexp2(hi[j]); }
;             }
;             float* d = buf + arr * TC * 64 + tt * 64 + c8 * 8;
;             *(f32x4*)d = lo; *(f32x4*)(d + 4) = hi;
;         }
;     }
; }
.Lsw_2:
	s_and_saveexec_b64 s[26:27], s[4:5]
	s_cbranch_execz .Lsw_2_k1
	v_lshlrev_b32_e32 v16, 16, v84
	v_and_b32_e32 v17, 0xffff0000, v84
	v_lshlrev_b32_e32 v18, 16, v85
	v_and_b32_e32 v19, 0xffff0000, v85
	v_lshlrev_b32_e32 v20, 16, v86
	v_and_b32_e32 v21, 0xffff0000, v86
	v_lshlrev_b32_e32 v22, 16, v87
	v_and_b32_e32 v23, 0xffff0000, v87
	s_and_saveexec_b64 s[28:29], s[22:23]
	s_xor_b64 s[28:29], exec, s[28:29]
	s_andn2_saveexec_b64 s[28:29], s[28:29]
	s_cbranch_execz .Lsw_2_noexp
	v_exp_f32_e32 v16, v16
	v_exp_f32_e32 v20, v20
	v_exp_f32_e32 v17, v17
	v_exp_f32_e32 v21, v21
	v_exp_f32_e32 v18, v18
	v_exp_f32_e32 v22, v22
	v_exp_f32_e32 v19, v19
	v_exp_f32_e32 v23, v23

; DEVINL float bflo(unsigned u) { return __uint_as_float(u << 16); }
; DEVINL float bfhi(unsigned u) { return __uint_as_float(u & 0xffff0000u); }
; DEVINL float fexp2(float x) { return __builtin_amdgcn_exp2f(x); }
; DEVINL void rw_stage_write(const u32x4 (&raw)[4], float* buf, int ht) {
;     const int rem = ht & 127, tt = rem >> 3, c8 = rem & 7;
; #pragma unroll
;     for (int k = 0; k < 4; ++k) {
;         const int arr = (ht >> 7) + 2 * k;
;         if (arr < 7) {
;             f32x4 lo = {bflo(raw[k][0]), bfhi(raw[k][0]), bflo(raw[k][1]), bfhi(raw[k][1])}, hi = {bflo(raw[k][2]), bfhi(raw[k][2]), bflo(raw[k][3]), bfhi(raw[k][3])};
;             if (arr == 1) {
; #pragma unroll
;                 for (int j = 0; j < 4; ++j) { lo[j] = fexp2(lo[j]); hi[j] = fexp2(hi[j]); }
;             }
;             float* d = buf + arr * TC * 64 + tt * 64 + c8 * 8;
;             *(f32x4*)d = lo; *(f32x4*)(d + 4) = hi;
;         }
;     }
; }
.Lsw_2_k1:
	s_or_b64 exec, exec, s[26:27]
	v_add_u32_e32 v16, v30, v157
	s_and_saveexec_b64 s[26:27], s[8:9]
	s_cbranch_execz .Lsw_2_k2
	v_lshlrev_b32_e32 v18, 16, v88
	v_and_b32_e32 v19, 0xffff0000, v88
	v_lshlrev_b32_e32 v20, 16, v89
	v_and_b32_e32 v21, 0xffff0000, v89
	v_lshlrev_b32_e32 v32, 16, v90
	v_and_b32_e32 v33, 0xffff0000, v90
	v_lshlrev_b32_e32 v34, 16, v91
	v_and_b32_e32 v35, 0xffff0000, v91
	ds_write_b128 v16, v[18:21] offset:8192
	ds_write_b128 v16, v[32:35] offset:8208
.Lsw_2_k2:
	s_or_b64 exec, exec, s[26:27]
	s_and_saveexec_b64 s[26:27], s[10:11]
	s_cbranch_execz .Lsw_2_k3
	v_lshlrev_b32_e32 v18, 16, v92
	v_and_b32_e32 v19, 0xffff0000, v92
	v_lshlrev_b32_e32 v20, 16, v93
	v_and_b32_e32 v21, 0xffff0000, v93
	v_lshlrev_b32_e32 v32, 16, v94
	v_and_b32_e32 v33, 0xffff0000, v94
	v_lshlrev_b32_e32 v34, 16, v95
	v_and_b32_e32 v35, 0xffff0000, v95
	ds_write_b128 v16, v[18:21] offset:16384
	ds_write_b128 v16, v[32:35] offset:16400
.Lsw_2_k3:
	s_or_b64 exec, exec, s[26:27]
	s_and_saveexec_b64 s[26:27], s[12:13]
	s_cbranch_execz .Lsw_2_end
	v_lshlrev_b32_e32 v16, 16, v96
	v_and_b32_e32 v17, 0xffff0000, v96
	v_lshlrev_b32_e32 v18, 16, v97
	v_and_b32_e32 v19, 0xffff0000, v97
	v_lshlrev_b32_e32 v20, 16, v98
	v_and_b32_e32 v21, 0xffff0000, v98
	v_lshlrev_b32_e32 v22, 16, v99
	v_and_b32_e32 v23, 0xffff0000, v99
	ds_write_b128 v30, v[16:19] offset:24576
	ds_write_b128 v30, v[20:23] offset:24592

; DEVINL float bflo(unsigned u) { return __uint_as_float(u << 16); }
; DEVINL float bfhi(unsigned u) { return __uint_as_float(u & 0xffff0000u); }
; DEVINL float fexp2(float x) { return __builtin_amdgcn_exp2f(x); }
; DEVINL void rw_stage_write(const u32x4 (&raw)[4], float* buf, int ht) {
;     const int rem = ht & 127, tt = rem >> 3, c8 = rem & 7;
; #pragma unroll
;     for (int k = 0; k < 4; ++k) {
;         const int arr = (ht >> 7) + 2 * k;
;         if (arr < 7) {
;             f32x4 lo = {bflo(raw[k][0]), bfhi(raw[k][0]), bflo(raw[k][1]), bfhi(raw[k][1])}, hi = {bflo(raw[k][2]), bfhi(raw[k][2]), bflo(raw[k][3]), bfhi(raw[k][3])};
;             if (arr == 1) {
; #pragma unroll
;                 for (int j = 0; j < 4; ++j) { lo[j] = fexp2(lo[j]); hi[j] = fexp2(hi[j]); }
;             }
;             float* d = buf + arr * TC * 64 + tt * 64 + c8 * 8;
;             *(f32x4*)d = lo; *(f32x4*)(d + 4) = hi;
;         }
;     }
; }
.Lsw_3:
	s_and_saveexec_b64 s[26:27], s[4:5]
	s_cbranch_execz .Lsw_3_k1
	v_lshlrev_b32_e32 v16, 16, v100
	v_and_b32_e32 v17, 0xffff0000, v100
	v_lshlrev_b32_e32 v18, 16, v101
	v_and_b32_e32 v19, 0xffff0000, v101
	v_lshlrev_b32_e32 v20, 16, v102
	v_and_b32_e32 v21, 0xffff0000, v102
	v_lshlrev_b32_e32 v22, 16, v103
	v_and_b32_e32 v23, 0xffff0000, v103
	s_and_saveexec_b64 s[28:29], s[22:23]
	s_xor_b64 s[28:29], exec, s[28:29]
	s_andn2_saveexec_b64 s[28:29], s[28:29]
	s_cbranch_execz .Lsw_3_noexp
	v_exp_f32_e32 v16, v16
	v_exp_f32_e32 v20, v20
	v_exp_f32_e32 v17, v17
	v_exp_f32_e32 v21, v21
	v_exp_f32_e32 v18, v18
	v_exp_f32_e32 v22, v22
	v_exp_f32_e32 v19, v19
	v_exp_f32_e32 v23, v23

; DEVINL float bflo(unsigned u) { return __uint_as_float(u << 16); }
; DEVINL float bfhi(unsigned u) { return __uint_as_float(u & 0xffff0000u); }
; DEVINL float fexp2(float x) { return __builtin_amdgcn_exp2f(x); }
; DEVINL void rw_stage_write(const u32x4 (&raw)[4], float* buf, int ht) {
;     const int rem = ht & 127, tt = rem >> 3, c8 = rem & 7;
; #pragma unroll
;     for (int k = 0; k < 4; ++k) {
;         const int arr = (ht >> 7) + 2 * k;
;         if (arr < 7) {
;             f32x4 lo = {bflo(raw[k][0]), bfhi(raw[k][0]), bflo(raw[k][1]), bfhi(raw[k][1])}, hi = {bflo(raw[k][2]), bfhi(raw[k][2]), bflo(raw[k][3]), bfhi(raw[k][3])};
;             if (arr == 1) {
; #pragma unroll
;                 for (int j = 0; j < 4; ++j) { lo[j] = fexp2(lo[j]); hi[j] = fexp2(hi[j]); }
;             }
;             float* d = buf + arr * TC * 64 + tt * 64 + c8 * 8;
;             *(f32x4*)d = lo; *(f32x4*)(d + 4) = hi;
;         }
;     }
; }
.Lsw_3_k1:
	s_or_b64 exec, exec, s[26:27]
	v_add_u32_e32 v16, v30, v157
	s_and_saveexec_b64 s[26:27], s[8:9]
	s_cbranch_execz .Lsw_3_k2
	v_lshlrev_b32_e32 v18, 16, v104
	v_and_b32_e32 v19, 0xffff0000, v104
	v_lshlrev_b32_e32 v20, 16, v105
	v_and_b32_e32 v21, 0xffff0000, v105
	v_lshlrev_b32_e32 v32, 16, v106
	v_and_b32_e32 v33, 0xffff0000, v106
	v_lshlrev_b32_e32 v34, 16, v107
	v_and_b32_e32 v35, 0xffff0000, v107
	ds_write_b128 v16, v[18:21] offset:8192
	ds_write_b128 v16, v[32:35] offset:8208
.Lsw_3_k2:
	s_or_b64 exec, exec, s[26:27]
	s_and_saveexec_b64 s[26:27], s[10:11]
	s_cbranch_execz .Lsw_3_k3
	v_lshlrev_b32_e32 v18, 16, v108
	v_and_b32_e32 v19, 0xffff0000, v108
	v_lshlrev_b32_e32 v20, 16, v109
	v_and_b32_e32 v21, 0xffff0000, v109
	v_lshlrev_b32_e32 v32, 16, v110
	v_and_b32_e32 v33, 0xffff0000, v110
	v_lshlrev_b32_e32 v34, 16, v111
	v_and_b32_e32 v35, 0xffff0000, v111
	ds_write_b128 v16, v[18:21] offset:16384
	ds_write_b128 v16, v[32:35] offset:16400
.Lsw_3_k3:
	s_or_b64 exec, exec, s[26:27]
	s_and_saveexec_b64 s[26:27], s[12:13]
	s_cbranch_execz .Lsw_3_end
	v_lshlrev_b32_e32 v16, 16, v112
	v_and_b32_e32 v17, 0xffff0000, v112
	v_lshlrev_b32_e32 v18, 16, v113
	v_and_b32_e32 v19, 0xffff0000, v113
	v_lshlrev_b32_e32 v20, 16, v114
	v_and_b32_e32 v21, 0xffff0000, v114
	v_lshlrev_b32_e32 v22, 16, v115
	v_and_b32_e32 v23, 0xffff0000, v115
	ds_write_b128 v30, v[16:19] offset:24576
	ds_write_b128 v30, v[20:23] offset:24592

; DEVINL void rwkv_scan(const Ctx& c, int layer, int b, int hd, const unsigned* cnt3, int nP, float* lds) {
;     ...
;             if (ch + 2 < NCH) {
.LBB0_335:
	s_cmpk_gt_u32 s38, 130
	s_cbranch_scc0 .LBB0_326
	s_branch .LBB0_336

; DEVINL void rwkv_scan(const Ctx& c, int layer, int b, int hd, const unsigned* cnt3, int nP, float* lds) {
;     ...
;             if (ch + 2 < NCH) {
;                 const unsigned need = (unsigned)(layer * 16 + (ch + 2) / (7 * nP) + 1);
;                 if (need > have) { rw_wait_ready(cnt3, need, nP); have = need; }
.LBB0_326:
	s_add_i32 s50, s38, 5
	s_mul_hi_u32 s26, s50, s39
	s_mul_i32 s27, s26, s37
	s_sub_i32 s27, s50, s27
	s_add_i32 s28, s26, 1
	s_sub_i32 s29, s27, s37
	s_cmp_ge_u32 s27, s37
	s_cselect_b32 s26, s28, s26
	s_cselect_b32 s27, s29, s27
	s_add_i32 s28, s26, 1
	s_cmp_ge_u32 s27, s37
	s_cselect_b32 s51, s28, s26
	s_add_i32 s51, s51, s36
	v_cmp_gt_u32_e32 vcc, s51, v171
	s_and_saveexec_b64 s[26:27], vcc
	s_cbranch_execz .LBB0_342
	s_mov_b32 s66, 0
	s_branch .LBB0_329

; DEVINL void rw_wait_ready(const unsigned* cnt3, unsigned need, int nP) {
;     for (int j = 0; j < nP; ++j)
;         while (__hip_atomic_load(cnt3 + j, __ATOMIC_RELAXED, __HIP_MEMORY_SCOPE_AGENT) < need) __builtin_amdgcn_s_sleep(8);
;     __builtin_amdgcn_fence(__ATOMIC_ACQUIRE, "agent");
;     asm volatile("s_waitcnt vmcnt(0)" ::: "memory");
; DEVINL void rwkv_scan(const Ctx& c, int layer, int b, int hd, const unsigned* cnt3, int nP, float* lds) {
;     ...
;             if (ch >= 1) {
.LBB0_330:
	s_sleep 8
	global_load_dword v16, v65, s[28:29] sc1
	s_waitcnt vmcnt(0)
	v_cmp_gt_u32_e32 vcc, s51, v16
	s_cbranch_vccnz .LBB0_330
	s_branch .LBB0_328
.LBB0_336:
	s_cmp_eq_u32 s38, 0
	s_cbranch_scc1 .LBB0_338

; DEVINL void rw_stage_load(u32x4 (&raw)[4], const bf16_t* rwbase, int t0, int hd, int ht) {
;     const int rem = ht & 127, tt = rem >> 3, c8 = rem & 7;
; #pragma unroll
;     for (int k = 0; k < 4; ++k) {
;         const int arr = (ht >> 7) + 2 * k;
;         if (arr < 7) raw[k] = *(const u32x4*)(rwbase + (size_t)arr * T * 512 + (size_t)(t0 + tt) * 512 + hd * 64 + c8 * 8);
;     }
; }
; DEVINL void rwkv_scan(const Ctx& c, int layer, int b, int hd, const unsigned* cnt3, int nP, float* lds) {
;     ...
;                 rw_stage_load(raw, rwbase, b * L + (ch + 2) * TC, hd, ht);
.LBB0_342:
	s_or_b64 exec, exec, s[26:27]
	v_lshl_add_u32 v16, s50, 4, v151
	v_ashrrev_i32_e32 v17, 31, v16
	v_lshlrev_b64 v[16:17], 10, v[16:17]
	v_lshl_add_u64 v[16:17], v[134:135], 0, v[16:17]
	s_and_b32 s27, s38, 3
	s_cmp_eq_u32 s27, 0
	s_cbranch_scc1 .Lsl_0
	s_cmp_eq_u32 s27, 1
	s_cbranch_scc1 .Lsl_1
	s_cmp_eq_u32 s27, 2
	s_cbranch_scc1 .Lsl_2
	s_branch .Lsl_3
.Lsl_0:
	s_and_saveexec_b64 s[26:27], s[14:15]
	s_cbranch_execz .Lsl_0_0
	v_lshl_add_u64 v[0:1], v[16:17], 0, v[136:137]
	global_load_dwordx4 v[0:3], v[0:1], off
.Lsl_0_0:
	s_or_b64 exec, exec, s[26:27]
	s_and_saveexec_b64 s[26:27], s[16:17]
	s_cbranch_execz .Lsl_0_1
	v_lshl_add_u64 v[4:5], v[16:17], 0, v[138:139]
	global_load_dwordx4 v[4:7], v[4:5], off
.Lsl_0_1:
	s_or_b64 exec, exec, s[26:27]
	s_and_saveexec_b64 s[26:27], s[18:19]
	s_cbranch_execz .Lsl_0_2
	v_lshl_add_u64 v[8:9], v[16:17], 0, v[140:141]
	global_load_dwordx4 v[8:11], v[8:9], off
.Lsl_0_2:
	s_or_b64 exec, exec, s[26:27]
	s_and_saveexec_b64 s[26:27], s[20:21]
	s_cbranch_execz .Lsl_0_3
	v_lshl_add_u64 v[12:13], v[16:17], 0, v[142:143]
	global_load_dwordx4 v[12:15], v[12:13], off

; DEVINL void rwkv_scan(const Ctx& c, int layer, int b, int hd, const unsigned* cnt3, int nP, float* lds) {
;     ...
;             if (ch >= 1) {
.LBB0_350:
	s_cmp_eq_u32 s38, 0
	s_cbranch_scc0 .LBB0_337
	s_branch .LBB0_338
